# attention: K-tile MFMAs no longer wait for the K tile just issued behind them (hipcc vmcnt(0) -> LDS wait only), on top of lean v-sweep + LN2 preload + P6 epilogue prefetch
# baseline (speedup 1.0000x reference)
.LBB0_222:
	v_cndmask_b32_e64 v3, 0, 1, s[4:5]
	v_mov_b32_e32 v2, 0xff800000
	v_cmp_ne_u32_e64 s[6:7], 1, v3
	s_andn2_b64 vcc, exec, s[4:5]
	v_mov_b32_e32 v159, 0xff800000
	v_mov_b32_e32 v162, 0xff800000
	v_mov_b32_e32 v139, 0xff800000
	v_mov_b32_e32 v160, 0xff800000
	v_mov_b32_e32 v163, 0xff800000
	v_mov_b32_e32 v166, 0xff800000
	v_mov_b32_e32 v161, 0xff800000
	v_mov_b32_e32 v164, 0xff800000
	v_mov_b32_e32 v167, 0xff800000
	v_mov_b32_e32 v170, 0xff800000
	v_mov_b32_e32 v165, 0xff800000
	v_mov_b32_e32 v168, 0xff800000
	v_mov_b32_e32 v171, 0xff800000
	v_mov_b32_e32 v173, 0xff800000
	v_mov_b32_e32 v169, 0xff800000
	v_mov_b32_e32 v172, 0xff800000
	s_cbranch_vccnz .LBB0_224
	s_waitcnt vmcnt(8)
	v_add_u32_e32 v3, v152, v119
	ds_read_b128 v[4:7], v3
	v_add_u32_e32 v3, v152, v121
	ds_read_b128 v[44:47], v3
	v_add_u32_e32 v3, v152, v142
	ds_read_b128 v[40:43], v3
	v_add_u32_e32 v3, v152, v143
	s_sub_i32 s4, s11, 64
	ds_read_b128 v[36:39], v3
	v_add_u32_e32 v3, v152, v144
	ds_read_b128 v[32:35], v3
	v_add_u32_e32 v3, v152, v145
	v_or_b32_e32 v8, s4, v1
	v_mov_b32_e32 v9, v105
	ds_read_b128 v[28:31], v3
	v_add_u32_e32 v3, v152, v146
	v_lshlrev_b64 v[8:9], 8, v[8:9]
	ds_read_b128 v[24:27], v3
	v_add_u32_e32 v3, v152, v147
	v_lshl_add_u64 v[8:9], s[8:9], 0, v[8:9]
	ds_read_b128 v[20:23], v3
	s_waitcnt lgkmcnt(0)
	v_lshl_add_u64 v[8:9], v[8:9], 0, v[104:105]
	s_mov_b32 s5, m0
	s_mov_b32 m0, s15
	s_nop 0
	global_load_lds_dwordx4 v[8:9], off
	s_mov_b32 m0, s5
	v_or_b32_e32 v8, s4, v103
	v_mov_b32_e32 v9, v105
	v_lshlrev_b64 v[8:9], 8, v[8:9]
	v_lshl_add_u64 v[8:9], s[8:9], 0, v[8:9]
	v_mov_b32_e32 v137, v105
	v_lshl_add_u64 v[8:9], v[8:9], 0, v[136:137]
	s_mov_b32 s5, m0
	s_mov_b32 m0, s91
	s_nop 0
	global_load_lds_dwordx4 v[8:9], off
	s_mov_b32 m0, s5
	v_or_b32_e32 v8, s4, v107
	v_mov_b32_e32 v9, v105
	v_lshlrev_b64 v[8:9], 8, v[8:9]
	v_lshl_add_u64 v[8:9], s[8:9], 0, v[8:9]
	v_mov_b32_e32 v135, v105
	v_lshl_add_u64 v[8:9], v[8:9], 0, v[134:135]
	s_mov_b32 s5, m0
	s_mov_b32 m0, s26
	s_nop 0
	global_load_lds_dwordx4 v[8:9], off
	s_mov_b32 m0, s5
	v_or_b32_e32 v8, s4, v109
	v_mov_b32_e32 v9, v105
	v_lshlrev_b64 v[8:9], 8, v[8:9]
	v_lshl_add_u64 v[8:9], s[8:9], 0, v[8:9]
	v_mov_b32_e32 v133, v105
	v_lshl_add_u64 v[8:9], v[8:9], 0, v[132:133]
	s_mov_b32 s5, m0
	s_mov_b32 m0, s27
	s_nop 0
	global_load_lds_dwordx4 v[8:9], off
	s_mov_b32 m0, s5
	v_or_b32_e32 v8, s4, v111
	v_mov_b32_e32 v9, v105
	v_lshlrev_b64 v[8:9], 8, v[8:9]
	v_lshl_add_u64 v[8:9], s[8:9], 0, v[8:9]
	v_lshl_add_u64 v[8:9], v[8:9], 0, v[104:105]
	s_mov_b32 s5, m0
	s_mov_b32 m0, s28
	s_nop 0
	global_load_lds_dwordx4 v[8:9], off
	s_mov_b32 m0, s5
	v_or_b32_e32 v8, s4, v113
	v_mov_b32_e32 v9, v105
	v_lshlrev_b64 v[8:9], 8, v[8:9]
	v_lshl_add_u64 v[8:9], s[8:9], 0, v[8:9]
	v_mov_b32_e32 v131, v105
	v_lshl_add_u64 v[8:9], v[8:9], 0, v[130:131]
	s_mov_b32 s5, m0
	s_mov_b32 m0, s29
	s_nop 0
	global_load_lds_dwordx4 v[8:9], off
	s_mov_b32 m0, s5
	v_or_b32_e32 v8, s4, v115
	v_mov_b32_e32 v9, v105
	v_lshlrev_b64 v[8:9], 8, v[8:9]
	v_lshl_add_u64 v[8:9], s[8:9], 0, v[8:9]
	v_mov_b32_e32 v129, v105
	v_lshl_add_u64 v[8:9], v[8:9], 0, v[128:129]
	s_mov_b32 s5, m0
	s_mov_b32 m0, s30
	s_nop 0
	global_load_lds_dwordx4 v[8:9], off
	s_mov_b32 m0, s5
	v_or_b32_e32 v8, s4, v117
	v_mov_b32_e32 v9, v105
	v_lshlrev_b64 v[8:9], 8, v[8:9]
	v_lshl_add_u64 v[8:9], s[8:9], 0, v[8:9]
	v_mov_b32_e32 v127, v105
	v_lshl_add_u64 v[8:9], v[8:9], 0, v[126:127]
	s_mov_b32 s4, m0
	s_mov_b32 m0, s31
	s_nop 0
	global_load_lds_dwordx4 v[8:9], off
	s_mov_b32 m0, s4
	s_waitcnt lgkmcnt(0)
	v_mfma_f32_32x32x16_bf16 v[4:19], v[4:7], v[50:53], 0
	v_readlane_b32 s4, v243, 34
	v_readlane_b32 s5, v243, 35
	v_mfma_f32_32x32x16_bf16 v[4:19], v[44:47], v[90:93], v[4:19]
	v_mfma_f32_32x32x16_bf16 v[4:19], v[40:43], v[86:89], v[4:19]
	v_mfma_f32_32x32x16_bf16 v[4:19], v[36:39], v[82:85], v[4:19]
	v_mfma_f32_32x32x16_bf16 v[4:19], v[32:35], v[78:81], v[4:19]
	v_mfma_f32_32x32x16_bf16 v[4:19], v[28:31], v[74:77], v[4:19]
	v_mfma_f32_32x32x16_bf16 v[4:19], v[24:27], v[70:73], v[4:19]
	v_mfma_f32_32x32x16_bf16 v[4:19], v[20:23], v[66:69], v[4:19]
	s_nop 11
	v_cndmask_b32_e64 v159, v4, v154, s[4:5]
	v_readlane_b32 s4, v243, 36
	v_readlane_b32 s5, v243, 37
	s_nop 1
	v_cndmask_b32_e64 v162, v5, v154, s[4:5]
	v_readlane_b32 s4, v243, 38
	v_readlane_b32 s5, v243, 39
	s_nop 1
	v_cndmask_b32_e64 v139, v6, v154, s[4:5]
	v_readlane_b32 s4, v243, 40
	v_readlane_b32 s5, v243, 41
	s_nop 1
	v_cndmask_b32_e64 v160, v7, v154, s[4:5]
	v_readlane_b32 s4, v243, 42
	v_readlane_b32 s5, v243, 43
	s_nop 1
	v_cndmask_b32_e64 v163, v8, v154, s[4:5]
	v_readlane_b32 s4, v243, 44
	v_readlane_b32 s5, v243, 45
	s_nop 1
	v_cndmask_b32_e64 v166, v9, v154, s[4:5]
	v_readlane_b32 s4, v243, 46
	v_readlane_b32 s5, v243, 47
	s_nop 1
	v_cndmask_b32_e64 v161, v10, v154, s[4:5]
	v_readlane_b32 s4, v243, 48
	v_readlane_b32 s5, v243, 49
	s_nop 1
	v_cndmask_b32_e64 v164, v11, v154, s[4:5]
	v_readlane_b32 s4, v243, 50
	v_readlane_b32 s5, v243, 51
	s_nop 1
	v_cndmask_b32_e64 v167, v12, v154, s[4:5]
	v_readlane_b32 s4, v243, 52
	v_readlane_b32 s5, v243, 53
	s_nop 1
	v_cndmask_b32_e64 v170, v13, v154, s[4:5]
	v_readlane_b32 s4, v243, 54
	v_readlane_b32 s5, v243, 55
	s_nop 1
	v_cndmask_b32_e64 v165, v14, v154, s[4:5]
	v_readlane_b32 s4, v243, 56
	v_readlane_b32 s5, v243, 57
	s_nop 1
	v_cndmask_b32_e64 v168, v15, v154, s[4:5]
	v_readlane_b32 s4, v243, 58
	v_readlane_b32 s5, v243, 59
	s_nop 1
	v_cndmask_b32_e64 v171, v16, v154, s[4:5]
	v_readlane_b32 s4, v243, 60
	v_readlane_b32 s5, v243, 61
	s_nop 1
	v_cndmask_b32_e64 v173, v17, v154, s[4:5]
	v_readlane_b32 s4, v243, 62
	v_readlane_b32 s5, v243, 63
	s_nop 1
	v_cndmask_b32_e64 v169, v18, v154, s[4:5]
	v_readlane_b32 s4, v242, 0
	v_readlane_b32 s5, v242, 1
	s_nop 1
	v_cndmask_b32_e64 v172, v19, v154, s[4:5]
.LBB0_224:
	s_cmp_gt_u32 s78, 2
	s_cselect_b64 s[4:5], -1, 0
	s_cmp_lt_u32 s78, 3
	v_mov_b32_e32 v3, 0xff800000
	v_mov_b32_e32 v4, 0xff800000
	v_mov_b32_e32 v5, 0xff800000
	v_mov_b32_e32 v6, 0xff800000
	v_mov_b32_e32 v7, 0xff800000
	v_mov_b32_e32 v8, 0xff800000
	v_mov_b32_e32 v9, 0xff800000
	v_mov_b32_e32 v10, 0xff800000
	v_mov_b32_e32 v11, 0xff800000
	v_mov_b32_e32 v12, 0xff800000
	v_mov_b32_e32 v13, 0xff800000
	v_mov_b32_e32 v14, 0xff800000
	v_mov_b32_e32 v15, 0xff800000
	v_mov_b32_e32 v16, 0xff800000
	v_mov_b32_e32 v17, 0xff800000
	s_cbranch_scc1 .LBB0_226
	s_waitcnt vmcnt(8)
	v_add_u32_e32 v2, v152, v119
	v_add_u32_e32 v6, v152, v121
	ds_read_b128 v[2:5], v2 offset:8192
	ds_read_b128 v[42:45], v6 offset:8192
	v_add_u32_e32 v6, v152, v142
	ds_read_b128 v[38:41], v6 offset:8192
	v_add_u32_e32 v6, v152, v143
	ds_read_b128 v[34:37], v6 offset:8192
	v_add_u32_e32 v6, v152, v144
	ds_read_b128 v[30:33], v6 offset:8192
	v_add_u32_e32 v6, v152, v145
	ds_read_b128 v[26:29], v6 offset:8192
	v_add_u32_e32 v6, v152, v146
	ds_read_b128 v[22:25], v6 offset:8192
	v_add_u32_e32 v6, v152, v147
	s_sub_i32 s92, s11, 32
	ds_read_b128 v[18:21], v6 offset:8192
	v_or_b32_e32 v6, s92, v1
	v_mov_b32_e32 v7, v105
	v_lshlrev_b64 v[6:7], 8, v[6:7]
	v_lshl_add_u64 v[6:7], s[8:9], 0, v[6:7]
	s_waitcnt lgkmcnt(0)
	v_lshl_add_u64 v[6:7], v[6:7], 0, v[104:105]
	s_mov_b32 s93, m0
	s_mov_b32 m0, s33
	s_nop 0
	global_load_lds_dwordx4 v[6:7], off
	s_mov_b32 m0, s93
	v_or_b32_e32 v6, s92, v103
	v_mov_b32_e32 v7, v105
	v_lshlrev_b64 v[6:7], 8, v[6:7]
	v_lshl_add_u64 v[6:7], s[8:9], 0, v[6:7]
	v_mov_b32_e32 v137, v105
	v_lshl_add_u64 v[6:7], v[6:7], 0, v[136:137]
	s_mov_b32 s93, m0
	s_mov_b32 m0, s34
	s_nop 0
	global_load_lds_dwordx4 v[6:7], off
	s_mov_b32 m0, s93
	v_or_b32_e32 v6, s92, v107
	v_mov_b32_e32 v7, v105
	v_lshlrev_b64 v[6:7], 8, v[6:7]
	v_lshl_add_u64 v[6:7], s[8:9], 0, v[6:7]
	v_mov_b32_e32 v135, v105
	v_lshl_add_u64 v[6:7], v[6:7], 0, v[134:135]
	s_mov_b32 s93, m0
	s_mov_b32 m0, s35
	s_nop 0
	global_load_lds_dwordx4 v[6:7], off
	s_mov_b32 m0, s93
	v_or_b32_e32 v6, s92, v109
	v_mov_b32_e32 v7, v105
	v_lshlrev_b64 v[6:7], 8, v[6:7]
	v_lshl_add_u64 v[6:7], s[8:9], 0, v[6:7]
	v_mov_b32_e32 v133, v105
	v_lshl_add_u64 v[6:7], v[6:7], 0, v[132:133]
	s_mov_b32 s93, m0
	s_mov_b32 m0, s36
	s_nop 0
	global_load_lds_dwordx4 v[6:7], off
	s_mov_b32 m0, s93
	v_or_b32_e32 v6, s92, v111
	v_mov_b32_e32 v7, v105
	v_lshlrev_b64 v[6:7], 8, v[6:7]
	v_lshl_add_u64 v[6:7], s[8:9], 0, v[6:7]
	v_lshl_add_u64 v[6:7], v[6:7], 0, v[104:105]
	s_mov_b32 s93, m0
	s_mov_b32 m0, s37
	s_nop 0
	global_load_lds_dwordx4 v[6:7], off
	s_mov_b32 m0, s93
	v_or_b32_e32 v6, s92, v113
	v_mov_b32_e32 v7, v105
	v_lshlrev_b64 v[6:7], 8, v[6:7]
	v_lshl_add_u64 v[6:7], s[8:9], 0, v[6:7]
	v_mov_b32_e32 v131, v105
	v_lshl_add_u64 v[6:7], v[6:7], 0, v[130:131]
	s_mov_b32 s93, m0
	s_mov_b32 m0, s16
	s_nop 0
	global_load_lds_dwordx4 v[6:7], off
	s_mov_b32 m0, s93
	v_or_b32_e32 v6, s92, v115
	v_mov_b32_e32 v7, v105
	v_lshlrev_b64 v[6:7], 8, v[6:7]
	v_lshl_add_u64 v[6:7], s[8:9], 0, v[6:7]
	v_mov_b32_e32 v129, v105
	v_lshl_add_u64 v[6:7], v[6:7], 0, v[128:129]
	s_mov_b32 s93, m0
	s_mov_b32 m0, s17
	s_nop 0
	global_load_lds_dwordx4 v[6:7], off
	s_mov_b32 m0, s93
	v_or_b32_e32 v6, s92, v117
	v_mov_b32_e32 v7, v105
	v_lshlrev_b64 v[6:7], 8, v[6:7]
	v_lshl_add_u64 v[6:7], s[8:9], 0, v[6:7]
	v_mov_b32_e32 v127, v105
	v_lshl_add_u64 v[6:7], v[6:7], 0, v[126:127]
	s_mov_b32 s92, m0
	s_mov_b32 m0, s13
	s_nop 0
	global_load_lds_dwordx4 v[6:7], off
	s_mov_b32 m0, s92
	s_waitcnt lgkmcnt(0)
	v_mfma_f32_32x32x16_bf16 v[2:17], v[2:5], v[50:53], 0
	v_mfma_f32_32x32x16_bf16 v[2:17], v[42:45], v[90:93], v[2:17]
	v_mfma_f32_32x32x16_bf16 v[2:17], v[38:41], v[86:89], v[2:17]
	v_mfma_f32_32x32x16_bf16 v[2:17], v[34:37], v[82:85], v[2:17]
	v_mfma_f32_32x32x16_bf16 v[2:17], v[30:33], v[78:81], v[2:17]
	v_mfma_f32_32x32x16_bf16 v[2:17], v[26:29], v[74:77], v[2:17]
	v_mfma_f32_32x32x16_bf16 v[2:17], v[22:25], v[70:73], v[2:17]
	v_mfma_f32_32x32x16_bf16 v[2:17], v[18:21], v[66:69], v[2:17]
.LBB0_226:
	v_or_b32_e32 v19, s11, v1
	s_cmp_lg_u32 s94, 0
	v_mov_b32_e32 v18, 0xff800000
	s_cselect_b64 s[92:93], -1, 0
	s_cmp_eq_u32 s94, 0
	v_lshlrev_b32_e32 v140, 8, v19
	v_mov_b32_e32 v34, 0xff800000
	v_mov_b32_e32 v35, 0xff800000
	v_mov_b32_e32 v36, 0xff800000
	v_mov_b32_e32 v37, 0xff800000
	v_mov_b32_e32 v38, 0xff800000
	v_mov_b32_e32 v39, 0xff800000
	v_mov_b32_e32 v40, 0xff800000
	v_mov_b32_e32 v41, 0xff800000
	v_mov_b32_e32 v42, 0xff800000
	v_mov_b32_e32 v43, 0xff800000
	v_mov_b32_e32 v44, 0xff800000
	v_mov_b32_e32 v45, 0xff800000
	v_mov_b32_e32 v46, 0xff800000
	v_mov_b32_e32 v47, 0xff800000
	v_mov_b32_e32 v48, 0xff800000
	v_mov_b32_e32 v49, 0xff800000
	s_cbranch_scc1 .LBB0_228
	s_waitcnt vmcnt(8)
	v_add_u32_e32 v19, v152, v119
	ds_read_b128 v[32:35], v19
	v_add_u32_e32 v19, v152, v121
	ds_read_b128 v[94:97], v19
	v_add_u32_e32 v19, v152, v142
	ds_read_b128 v[62:65], v19
	v_add_u32_e32 v19, v152, v143
	ds_read_b128 v[58:61], v19
	v_add_u32_e32 v19, v152, v144
	ds_read_b128 v[54:57], v19
	v_add_u32_e32 v19, v152, v145
	ds_read_b128 v[28:31], v19
	v_add_u32_e32 v19, v152, v146
	v_mov_b32_e32 v141, v105
	ds_read_b128 v[24:27], v19
	v_add_u32_e32 v19, v152, v147
	v_lshl_add_u64 v[36:37], s[8:9], 0, v[140:141]
	ds_read_b128 v[20:23], v19
	s_waitcnt lgkmcnt(0)
	v_lshl_add_u64 v[36:37], v[36:37], 0, v[104:105]
	v_or_b32_e32 v19, s11, v103
	s_mov_b32 s94, m0
	s_mov_b32 m0, s15
	s_nop 0
	global_load_lds_dwordx4 v[36:37], off
	s_mov_b32 m0, s94
	v_lshlrev_b32_e32 v36, 8, v19
	v_mov_b32_e32 v37, v105
	v_lshl_add_u64 v[36:37], s[8:9], 0, v[36:37]
	v_mov_b32_e32 v137, v105
	v_lshl_add_u64 v[36:37], v[36:37], 0, v[136:137]
	v_or_b32_e32 v19, s11, v107
	s_mov_b32 s94, m0
	s_mov_b32 m0, s91
	s_nop 0
	global_load_lds_dwordx4 v[36:37], off
	s_mov_b32 m0, s94
	v_lshlrev_b32_e32 v36, 8, v19
	v_mov_b32_e32 v37, v105
	v_lshl_add_u64 v[36:37], s[8:9], 0, v[36:37]
	v_mov_b32_e32 v135, v105
	v_lshl_add_u64 v[36:37], v[36:37], 0, v[134:135]
	v_or_b32_e32 v19, s11, v109
	s_mov_b32 s94, m0
	s_mov_b32 m0, s26
	s_nop 0
	global_load_lds_dwordx4 v[36:37], off
	s_mov_b32 m0, s94
	v_lshlrev_b32_e32 v36, 8, v19
	v_mov_b32_e32 v37, v105
	v_lshl_add_u64 v[36:37], s[8:9], 0, v[36:37]
	v_mov_b32_e32 v133, v105
	v_lshl_add_u64 v[36:37], v[36:37], 0, v[132:133]
	v_or_b32_e32 v19, s11, v111
	s_mov_b32 s94, m0
	s_mov_b32 m0, s27
	s_nop 0
	global_load_lds_dwordx4 v[36:37], off
	s_mov_b32 m0, s94
	v_lshlrev_b32_e32 v36, 8, v19
	v_mov_b32_e32 v37, v105
	v_lshl_add_u64 v[36:37], s[8:9], 0, v[36:37]
	v_lshl_add_u64 v[36:37], v[36:37], 0, v[104:105]
	v_or_b32_e32 v19, s11, v113
	s_mov_b32 s94, m0
	s_mov_b32 m0, s28
	s_nop 0
	global_load_lds_dwordx4 v[36:37], off
	s_mov_b32 m0, s94
	v_lshlrev_b32_e32 v36, 8, v19
	v_mov_b32_e32 v37, v105
	v_lshl_add_u64 v[36:37], s[8:9], 0, v[36:37]
	v_mov_b32_e32 v131, v105
	v_lshl_add_u64 v[36:37], v[36:37], 0, v[130:131]
	v_or_b32_e32 v19, s11, v115
	s_mov_b32 s94, m0
	s_mov_b32 m0, s29
	s_nop 0
	global_load_lds_dwordx4 v[36:37], off
	s_mov_b32 m0, s94
	v_lshlrev_b32_e32 v36, 8, v19
	v_mov_b32_e32 v37, v105
	v_lshl_add_u64 v[36:37], s[8:9], 0, v[36:37]
	v_mov_b32_e32 v129, v105
	v_lshl_add_u64 v[36:37], v[36:37], 0, v[128:129]
	v_or_b32_e32 v19, s11, v117
	s_mov_b32 s94, m0
	s_mov_b32 m0, s30
	s_nop 0
	global_load_lds_dwordx4 v[36:37], off
	s_mov_b32 m0, s94
	v_lshlrev_b32_e32 v36, 8, v19
	v_mov_b32_e32 v37, v105
	v_lshl_add_u64 v[36:37], s[8:9], 0, v[36:37]
	v_mov_b32_e32 v127, v105
	v_lshl_add_u64 v[36:37], v[36:37], 0, v[126:127]
	s_mov_b32 s8, m0
	s_mov_b32 m0, s31
	s_nop 0
	global_load_lds_dwordx4 v[36:37], off
	s_mov_b32 m0, s8
	s_waitcnt lgkmcnt(0)
	v_mfma_f32_32x32x16_bf16 v[34:49], v[32:35], v[50:53], 0
	v_mfma_f32_32x32x16_bf16 v[34:49], v[94:97], v[90:93], v[34:49]
	v_mfma_f32_32x32x16_bf16 v[34:49], v[62:65], v[86:89], v[34:49]
	v_mfma_f32_32x32x16_bf16 v[34:49], v[58:61], v[82:85], v[34:49]
	v_mfma_f32_32x32x16_bf16 v[34:49], v[54:57], v[78:81], v[34:49]
	v_mfma_f32_32x32x16_bf16 v[34:49], v[28:31], v[74:77], v[34:49]
	v_mfma_f32_32x32x16_bf16 v[34:49], v[24:27], v[70:73], v[34:49]
	v_mfma_f32_32x32x16_bf16 v[34:49], v[20:23], v[66:69], v[34:49]
.LBB0_228:
	s_lshl_b64 s[8:9], s[24:25], 19
	s_lshl_b64 s[8:9], s[8:9], 1
	v_readlane_b32 s24, v243, 26
	s_add_u32 s8, s24, s8
	v_readlane_b32 s24, v243, 27
	s_addc_u32 s9, s24, s9
	s_cmp_lg_u32 s78, 0
	s_cselect_b64 s[94:95], -1, 0
	s_cmp_eq_u32 s78, 0
	v_mov_b32_e32 v19, 0xff800000
	v_mov_b32_e32 v20, 0xff800000
	v_mov_b32_e32 v21, 0xff800000
	v_mov_b32_e32 v22, 0xff800000
	v_mov_b32_e32 v23, 0xff800000
	v_mov_b32_e32 v24, 0xff800000
	v_mov_b32_e32 v25, 0xff800000
	v_mov_b32_e32 v26, 0xff800000
	v_mov_b32_e32 v27, 0xff800000
	v_mov_b32_e32 v28, 0xff800000
	v_mov_b32_e32 v29, 0xff800000
	v_mov_b32_e32 v30, 0xff800000
	v_mov_b32_e32 v31, 0xff800000
	v_mov_b32_e32 v32, 0xff800000
	v_mov_b32_e32 v33, 0xff800000
	s_cbranch_scc1 .LBB0_230
	s_waitcnt vmcnt(8)
	v_add_u32_e32 v18, v152, v119
	ds_read_b128 v[18:21], v18 offset:8192
	v_add_u32_e32 v22, v152, v121
	ds_read_b128 v[54:57], v22 offset:8192
	v_add_u32_e32 v58, v152, v142
	v_mov_b32_e32 v141, v105
	v_add_u32_e32 v62, v152, v147
	s_movk_i32 s96, 0xe000
	s_mov_b32 s97, -1
	s_waitcnt lgkmcnt(0)
	v_mfma_f32_32x32x16_bf16 v[18:33], v[18:21], v[50:53], 0
	v_mfma_f32_32x32x16_bf16 v[18:33], v[54:57], v[90:93], v[18:33]
	ds_read_b128 v[54:57], v58 offset:8192
	v_add_u32_e32 v58, v152, v143
	ds_read_b128 v[58:61], v58 offset:8192
	s_waitcnt lgkmcnt(1)
	v_mfma_f32_32x32x16_bf16 v[18:33], v[54:57], v[86:89], v[18:33]
	v_add_u32_e32 v54, v152, v144
	ds_read_b128 v[54:57], v54 offset:8192
	s_waitcnt lgkmcnt(1)
	v_mfma_f32_32x32x16_bf16 v[18:33], v[58:61], v[82:85], v[18:33]
	v_lshl_add_u64 v[58:59], s[8:9], 0, v[140:141]
	v_lshlrev_b32_e32 v60, 1, v120
	v_mov_b32_e32 v61, v105
	v_lshl_add_u64 v[94:95], v[58:59], 0, v[60:61]
	v_add_u32_e32 v58, v152, v145
	ds_read_b128 v[58:61], v58 offset:8192
	v_lshl_add_u64 v[96:97], v[94:95], 0, s[96:97]
	s_waitcnt lgkmcnt(1)
	v_mfma_f32_32x32x16_bf16 v[18:33], v[54:57], v[78:81], v[18:33]
	v_add_u32_e32 v54, v152, v146
	ds_read_b128 v[54:57], v54 offset:8192
	ds_read_b128 v[62:65], v62 offset:8192
	s_movk_i32 s96, 0xe400
	s_mov_b32 s97, -1
	s_waitcnt lgkmcnt(0)
	s_mov_b32 s24, m0
	s_mov_b32 m0, s33
	s_nop 0
	global_load_lds_dwordx4 v[96:97], off
	s_mov_b32 m0, s24
	s_waitcnt lgkmcnt(2)
	v_mfma_f32_32x32x16_bf16 v[18:33], v[58:61], v[74:77], v[18:33]
	v_lshl_add_u64 v[58:59], v[94:95], 0, s[96:97]
	s_movk_i32 s96, 0xe800
	s_mov_b32 s97, -1
	s_mov_b32 s24, m0
	s_mov_b32 m0, s34
	s_nop 0
	global_load_lds_dwordx4 v[58:59], off
	s_mov_b32 m0, s24
	v_lshl_add_u64 v[58:59], v[94:95], 0, s[96:97]
	s_movk_i32 s96, 0xec00
	s_mov_b32 s97, -1
	s_waitcnt lgkmcnt(1)
	v_mfma_f32_32x32x16_bf16 v[18:33], v[54:57], v[70:73], v[18:33]
	s_mov_b32 s24, m0
	s_mov_b32 m0, s35
	s_nop 0
	global_load_lds_dwordx4 v[58:59], off
	s_mov_b32 m0, s24
	v_lshl_add_u64 v[58:59], v[94:95], 0, s[96:97]
	s_movk_i32 s96, 0xf000
	s_mov_b32 s97, -1
	s_mov_b32 s24, m0
	s_mov_b32 m0, s36
	s_nop 0
	global_load_lds_dwordx4 v[58:59], off
	s_mov_b32 m0, s24
	v_lshl_add_u64 v[58:59], v[94:95], 0, s[96:97]
	s_movk_i32 s96, 0xf400
	s_mov_b32 s97, -1
	s_waitcnt lgkmcnt(0)
	v_mfma_f32_32x32x16_bf16 v[18:33], v[62:65], v[66:69], v[18:33]
	v_lshl_add_u64 v[54:55], v[94:95], 0, s[96:97]
	s_movk_i32 s96, 0xf800
	s_mov_b32 s24, m0
	s_mov_b32 m0, s37
	s_nop 0
	global_load_lds_dwordx4 v[58:59], off
	s_mov_b32 m0, s24
	s_mov_b32 s97, -1
	s_mov_b32 s24, m0
	s_mov_b32 m0, s16
	s_nop 0
	global_load_lds_dwordx4 v[54:55], off
	s_mov_b32 m0, s24
	v_lshl_add_u64 v[54:55], v[94:95], 0, s[96:97]
	s_movk_i32 s96, 0xfc00
	s_mov_b32 s24, m0
	s_mov_b32 m0, s17
	s_nop 0
	global_load_lds_dwordx4 v[54:55], off
	s_mov_b32 m0, s24
	s_mov_b32 s97, -1
	v_lshl_add_u64 v[54:55], v[94:95], 0, s[96:97]
	s_mov_b32 s24, m0
	s_mov_b32 m0, s13
	s_nop 0
	global_load_lds_dwordx4 v[54:55], off
	s_mov_b32 m0, s24

.LBB0_233:
	v_add_u32_e32 v54, v152, v119
	ds_read_b128 v[54:57], v54
	v_add_u32_e32 v58, v152, v121
	ds_read_b128 v[174:177], v58
	v_add_u32_e32 v96, v152, v142
	ds_read_b128 v[178:181], v96
	v_add_u32_e32 v127, v152, v144
	v_add_u32_e32 v129, v152, v145
	v_add_u32_e32 v131, v152, v146
	v_add_u32_e32 v133, v152, v147
	s_waitcnt lgkmcnt(0)
	v_mfma_f32_32x32x16_bf16 v[50:65], v[54:57], v[50:53], 0
	s_mov_b32 s24, 0xff800000
	v_max3_f32 v135, v159, s24, v162
	v_mov_b32_e32 v141, v105
	v_lshlrev_b32_e32 v94, 1, v120
	v_mov_b32_e32 v95, v105
	s_mov_b64 s[96:97], 0x400
	v_mfma_f32_32x32x16_bf16 v[50:65], v[174:177], v[90:93], v[50:65]
	v_add_u32_e32 v90, v152, v143
	ds_read_b128 v[90:93], v90
	v_lshl_add_u64 v[96:97], s[8:9], 0, v[140:141]
	v_mfma_f32_32x32x16_bf16 v[50:65], v[178:181], v[86:89], v[50:65]
	ds_read_b128 v[86:89], v127
	ds_read_b128 v[174:177], v129
	ds_read_b128 v[178:181], v131
	ds_read_b128 v[182:185], v133
	v_max3_f32 v127, v135, v139, v160
	v_max3_f32 v127, v127, v163, v166
	s_waitcnt lgkmcnt(0)
	s_waitcnt lgkmcnt(4)
	v_mfma_f32_32x32x16_bf16 v[50:65], v[90:93], v[82:85], v[50:65]
	v_lshl_add_u64 v[82:83], v[96:97], 0, v[94:95]
	s_mov_b32 s24, m0
	s_mov_b32 m0, s15
	s_nop 0
	global_load_lds_dwordx4 v[82:83], off
	s_mov_b32 m0, s24
	v_lshl_add_u64 v[84:85], v[82:83], 0, s[96:97]
	s_mov_b64 s[96:97], 0x800
	s_mov_b32 s24, m0
	s_mov_b32 m0, s91
	s_nop 0
	global_load_lds_dwordx4 v[84:85], off
	s_mov_b32 m0, s24
	v_lshl_add_u64 v[90:91], v[82:83], 0, s[96:97]
	s_mov_b32 s24, m0
	s_mov_b32 m0, s26
	s_nop 0
	global_load_lds_dwordx4 v[90:91], off
	s_mov_b32 m0, s24
	s_waitcnt lgkmcnt(3)
	v_mfma_f32_32x32x16_bf16 v[50:65], v[86:89], v[78:81], v[50:65]
	v_max3_f32 v78, v127, v161, v164
	v_max3_f32 v78, v78, v167, v170
	v_max3_f32 v78, v78, v165, v168
	v_max3_f32 v78, v78, v171, v173
	v_lshl_add_u64 v[92:93], v[82:83], 0, s[80:81]
	s_mov_b32 s24, m0
	s_mov_b32 m0, s27
	s_nop 0
	global_load_lds_dwordx4 v[92:93], off
	s_mov_b32 m0, s24
	v_lshl_add_u64 v[96:97], v[82:83], 0, s[82:83]
	s_waitcnt lgkmcnt(2)
	v_mfma_f32_32x32x16_bf16 v[50:65], v[174:177], v[74:77], v[50:65]
	v_max3_f32 v74, v78, v169, v172
	v_max3_f32 v74, v74, v2, v3
	v_max3_f32 v74, v74, v4, v5
	v_max3_f32 v74, v74, v6, v7
	v_max3_f32 v74, v74, v8, v9
	v_max3_f32 v74, v74, v10, v11
	s_mov_b32 s24, m0
	s_mov_b32 m0, s28
	s_nop 0
	global_load_lds_dwordx4 v[96:97], off
	s_mov_b32 m0, s24
	s_waitcnt lgkmcnt(1)
	v_mfma_f32_32x32x16_bf16 v[50:65], v[178:181], v[70:73], v[50:65]
	v_max3_f32 v70, v74, v12, v13
	v_max3_f32 v70, v70, v14, v15
	v_max3_f32 v70, v70, v16, v17
	v_max3_f32 v70, v70, v34, v35
	v_max3_f32 v70, v70, v36, v37
	v_max3_f32 v70, v70, v38, v39
	v_max3_f32 v70, v70, v40, v41
	s_waitcnt lgkmcnt(0)
	v_mfma_f32_32x32x16_bf16 v[50:65], v[182:185], v[66:69], v[50:65]
	v_add_u32_e32 v92, v153, v148
	v_add_u32_e32 v88, v153, v149
	v_add_u32_e32 v93, v153, v150
	v_add_u32_e32 v127, v153, v151
	s_nop 7
	v_cndmask_b32_e64 v66, v50, v154, s[38:39]
	v_cndmask_b32_e64 v66, v66, v50, s[40:41]
	v_max3_f32 v50, v70, v42, v43
	v_max3_f32 v50, v50, v44, v45
	v_max3_f32 v50, v50, v46, v47
	v_max3_f32 v50, v50, v48, v49
	v_max3_f32 v50, v50, v18, v19
	v_max3_f32 v50, v50, v20, v21
	v_max3_f32 v50, v50, v22, v23
	v_max3_f32 v50, v50, v24, v25
	v_max3_f32 v50, v50, v26, v27
	v_max3_f32 v50, v50, v28, v29
	v_max3_f32 v50, v50, v30, v31
	v_cndmask_b32_e64 v67, v154, v51, s[40:41]
	v_max3_f32 v50, v50, v32, v33
	v_cndmask_b32_e64 v52, v52, v154, s[42:43]
	v_cndmask_b32_e64 v53, v53, v154, s[44:45]
	v_max3_f32 v50, v50, v66, v67
	v_cndmask_b32_e64 v54, v54, v154, s[46:47]
	v_cndmask_b32_e64 v55, v55, v154, s[48:49]
	v_max3_f32 v50, v50, v52, v53
	v_cndmask_b32_e64 v56, v56, v154, s[50:51]
	v_cndmask_b32_e64 v57, v57, v154, s[52:53]
	v_max3_f32 v50, v50, v54, v55
	v_cndmask_b32_e64 v58, v58, v154, s[54:55]
	v_cndmask_b32_e64 v59, v59, v154, s[56:57]
	v_max3_f32 v50, v50, v56, v57
	v_cndmask_b32_e64 v60, v60, v154, s[58:59]
	v_cndmask_b32_e64 v61, v61, v154, s[60:61]
	v_max3_f32 v50, v50, v58, v59
	v_cndmask_b32_e64 v62, v62, v154, s[62:63]
	v_cndmask_b32_e64 v63, v63, v154, s[64:65]
	v_max3_f32 v50, v50, v60, v61
	v_cndmask_b32_e64 v64, v64, v154, s[66:67]
	v_cndmask_b32_e64 v65, v65, v154, s[68:69]
	v_max3_f32 v50, v50, v62, v63
	v_and_b32_e32 v51, 64, v155
	v_max3_f32 v68, v50, v64, v65
	v_xor_b32_e32 v50, 32, v155
	v_add_u32_e32 v51, 64, v51
	v_cmp_lt_i32_e32 vcc, v50, v51
	s_nop 1
	v_cndmask_b32_e32 v50, v155, v50, vcc
	v_lshlrev_b32_e32 v69, 2, v50
	ds_bpermute_b32 v70, v69, v68
	v_lshl_add_u64 v[50:51], v[82:83], 0, s[84:85]
	s_mov_b32 s24, m0
	s_mov_b32 m0, s29
	s_nop 0
	global_load_lds_dwordx4 v[50:51], off
	s_mov_b32 m0, s24
	v_lshl_add_u64 v[50:51], v[82:83], 0, s[86:87]
	s_mov_b32 s24, m0
	s_mov_b32 m0, s30
	s_nop 0
	global_load_lds_dwordx4 v[50:51], off
	s_mov_b32 m0, s24
	s_waitcnt lgkmcnt(0)
	v_max_f32_e32 v50, v70, v70
	v_max_f32_e32 v50, v68, v50
	v_mul_f32_e32 v50, 0x3e0293ee, v50
	v_mul_f32_e32 v70, 0x3fb8aa3b, v158
	v_max_f32_e32 v71, v50, v70
	v_fma_f32 v50, v159, s90, -v71
	v_exp_f32_e32 v72, v50
	v_fma_f32 v50, v162, s90, -v71
	v_exp_f32_e32 v73, v50
	v_lshl_add_u64 v[50:51], v[82:83], 0, s[88:89]
	s_mov_b32 s24, m0
	s_mov_b32 m0, s31
	s_nop 0
	global_load_lds_dwordx4 v[50:51], off
	s_mov_b32 m0, s24
	v_fma_f32 v51, v139, s90, -v71
	v_exp_f32_e32 v74, v51
	v_fma_f32 v51, v160, s90, -v71
	v_exp_f32_e32 v75, v51
	v_fma_f32 v51, v163, s90, -v71
	v_add_f32_e32 v50, 0, v72
	v_exp_f32_e32 v76, v51
	v_fma_f32 v51, v166, s90, -v71
	v_add_f32_e32 v50, v73, v50
	v_exp_f32_e32 v77, v51
	v_fma_f32 v51, v161, s90, -v71
	v_add_f32_e32 v50, v74, v50
	v_exp_f32_e32 v78, v51
	v_fma_f32 v51, v164, s90, -v71
	v_add_f32_e32 v50, v75, v50
	v_exp_f32_e32 v79, v51
	v_fma_f32 v51, v167, s90, -v71
	v_add_f32_e32 v50, v76, v50
	v_exp_f32_e32 v80, v51
	v_fma_f32 v51, v170, s90, -v71
	v_add_f32_e32 v50, v77, v50
	v_exp_f32_e32 v81, v51
	v_fma_f32 v51, v165, s90, -v71
	v_add_f32_e32 v50, v78, v50
	v_exp_f32_e32 v82, v51
	v_fma_f32 v51, v168, s90, -v71
	v_add_f32_e32 v50, v79, v50
	v_exp_f32_e32 v83, v51
	v_fma_f32 v51, v171, s90, -v71
	v_add_f32_e32 v50, v80, v50
	v_exp_f32_e32 v84, v51
	v_fma_f32 v51, v173, s90, -v71
	v_add_f32_e32 v50, v81, v50
	v_exp_f32_e32 v85, v51
	v_fma_f32 v51, v169, s90, -v71
	v_add_f32_e32 v50, v82, v50
	v_exp_f32_e32 v86, v51
	v_fma_f32 v51, v172, s90, -v71
	v_add_f32_e32 v50, v83, v50
	v_exp_f32_e32 v87, v51
	v_fma_f32 v2, v2, s90, -v71
	v_add_f32_e32 v50, v84, v50
	v_exp_f32_e32 v91, v2
	v_fma_f32 v2, v3, s90, -v71
	v_add_f32_e32 v50, v85, v50
	v_exp_f32_e32 v96, v2
	v_fma_f32 v3, v4, s90, -v71
	v_add_f32_e32 v2, v86, v50
	v_exp_f32_e32 v97, v3
	v_fma_f32 v3, v5, s90, -v71
	v_add_f32_e32 v2, v87, v2
	v_exp_f32_e32 v129, v3
	v_fma_f32 v3, v6, s90, -v71
	v_add_f32_e32 v2, v91, v2
	v_exp_f32_e32 v131, v3
	v_fma_f32 v3, v7, s90, -v71
	v_add_f32_e32 v2, v96, v2
	v_exp_f32_e32 v133, v3
	v_fma_f32 v3, v8, s90, -v71
	v_add_f32_e32 v2, v97, v2
	v_exp_f32_e32 v135, v3
	v_fma_f32 v3, v9, s90, -v71
	v_add_f32_e32 v2, v129, v2
	v_exp_f32_e32 v137, v3
	v_fma_f32 v3, v10, s90, -v71
	v_add_f32_e32 v2, v131, v2
	v_exp_f32_e32 v139, v3
	v_fma_f32 v3, v11, s90, -v71
	v_add_f32_e32 v2, v133, v2
	v_exp_f32_e32 v140, v3
	v_fma_f32 v3, v12, s90, -v71
	v_add_f32_e32 v2, v135, v2
	v_exp_f32_e32 v141, v3
	v_fma_f32 v3, v13, s90, -v71
	v_add_f32_e32 v2, v137, v2
	v_exp_f32_e32 v158, v3
	v_fma_f32 v3, v14, s90, -v71
	v_add_f32_e32 v2, v139, v2
	v_exp_f32_e32 v159, v3
	v_fma_f32 v3, v15, s90, -v71
	v_add_f32_e32 v2, v140, v2
	v_exp_f32_e32 v160, v3
	v_fma_f32 v3, v16, s90, -v71
	v_add_f32_e32 v2, v141, v2
	v_exp_f32_e32 v161, v3
	v_fma_f32 v3, v17, s90, -v71
	v_add_f32_e32 v2, v158, v2
	v_exp_f32_e32 v162, v3
	v_fma_f32 v3, v34, s90, -v71
	v_add_f32_e32 v2, v159, v2
	v_exp_f32_e32 v163, v3
	v_fma_f32 v3, v35, s90, -v71
	v_add_f32_e32 v2, v160, v2
	v_exp_f32_e32 v164, v3
	v_fma_f32 v3, v36, s90, -v71
	v_add_f32_e32 v2, v161, v2
	v_exp_f32_e32 v165, v3
	v_fma_f32 v3, v37, s90, -v71
	v_add_f32_e32 v2, v162, v2
	v_exp_f32_e32 v166, v3
	v_fma_f32 v3, v38, s90, -v71
	v_add_f32_e32 v2, v163, v2
	v_exp_f32_e32 v167, v3
	v_fma_f32 v3, v39, s90, -v71
	v_add_f32_e32 v2, v164, v2
	v_exp_f32_e32 v168, v3
	v_fma_f32 v3, v40, s90, -v71
	v_add_f32_e32 v2, v165, v2
	v_exp_f32_e32 v169, v3
	v_fma_f32 v3, v41, s90, -v71
	v_add_f32_e32 v2, v166, v2
	v_exp_f32_e32 v170, v3
	v_fma_f32 v3, v42, s90, -v71
	v_add_f32_e32 v2, v167, v2
	v_exp_f32_e32 v171, v3
	v_fma_f32 v3, v43, s90, -v71
	v_add_f32_e32 v2, v168, v2
	v_exp_f32_e32 v172, v3
	v_fma_f32 v3, v44, s90, -v71
	v_add_f32_e32 v2, v169, v2
	v_exp_f32_e32 v173, v3
	v_fma_f32 v3, v45, s90, -v71
	v_add_f32_e32 v2, v170, v2
	v_exp_f32_e32 v174, v3
	v_fma_f32 v3, v46, s90, -v71
	v_add_f32_e32 v2, v171, v2
	v_exp_f32_e32 v175, v3
	v_fma_f32 v3, v47, s90, -v71
	v_add_f32_e32 v2, v172, v2
	v_exp_f32_e32 v176, v3
	v_fma_f32 v3, v48, s90, -v71
	v_add_f32_e32 v2, v173, v2
	v_exp_f32_e32 v177, v3
	v_fma_f32 v3, v49, s90, -v71
	v_add_f32_e32 v2, v174, v2
	v_exp_f32_e32 v178, v3
	v_fma_f32 v3, v18, s90, -v71
	v_add_f32_e32 v2, v175, v2
	v_exp_f32_e32 v179, v3
	v_fma_f32 v3, v19, s90, -v71
	v_add_f32_e32 v2, v176, v2
	v_exp_f32_e32 v180, v3
	v_fma_f32 v3, v20, s90, -v71
	v_add_f32_e32 v2, v177, v2
	v_exp_f32_e32 v181, v3
	v_fma_f32 v3, v21, s90, -v71
	v_add_f32_e32 v2, v178, v2
	v_exp_f32_e32 v182, v3
	v_fma_f32 v3, v22, s90, -v71
	v_add_f32_e32 v2, v179, v2
	v_exp_f32_e32 v183, v3
	v_fma_f32 v3, v23, s90, -v71
	v_add_f32_e32 v2, v180, v2
	v_exp_f32_e32 v184, v3
	v_fma_f32 v3, v24, s90, -v71
	v_add_f32_e32 v2, v181, v2
	v_exp_f32_e32 v185, v3
	v_fma_f32 v3, v25, s90, -v71
	v_add_f32_e32 v2, v182, v2
	v_exp_f32_e32 v186, v3
	v_fma_f32 v3, v26, s90, -v71
	v_add_f32_e32 v2, v183, v2
	v_exp_f32_e32 v187, v3
	v_fma_f32 v3, v27, s90, -v71
	v_add_f32_e32 v2, v184, v2
	v_exp_f32_e32 v188, v3
	v_add_f32_e32 v2, v185, v2
	v_add_f32_e32 v2, v186, v2
	v_add_f32_e32 v2, v187, v2
	v_add_f32_e32 v14, v188, v2
	v_fma_f32 v2, v28, s90, -v71
	v_exp_f32_e32 v189, v2
	v_fma_f32 v2, v29, s90, -v71
	v_exp_f32_e32 v190, v2
	v_fma_f32 v2, v30, s90, -v71
	v_exp_f32_e32 v191, v2
	v_fma_f32 v2, v66, s90, -v71
	v_exp_f32_e32 v16, v2
	v_fma_f32 v2, v67, s90, -v71
	v_exp_f32_e32 v17, v2
	v_fma_f32 v2, v52, s90, -v71
	v_exp_f32_e32 v18, v2
	v_fma_f32 v2, v53, s90, -v71
	v_exp_f32_e32 v66, v2
	v_fma_f32 v2, v54, s90, -v71
	v_exp_f32_e32 v67, v2
	v_fma_f32 v2, v55, s90, -v71
	v_exp_f32_e32 v68, v2
	v_fma_f32 v2, v56, s90, -v71
	v_exp_f32_e32 v89, v2
	v_fma_f32 v2, v57, s90, -v71
	v_exp_f32_e32 v90, v2
	v_fma_f32 v2, v58, s90, -v71
	v_exp_f32_e32 v195, v2
	v_fma_f32 v2, v59, s90, -v71
	v_exp_f32_e32 v197, v2
	v_fma_f32 v2, v60, s90, -v71
	v_exp_f32_e32 v202, v2
	v_fma_f32 v2, v61, s90, -v71
	v_exp_f32_e32 v203, v2
	v_fma_f32 v2, v62, s90, -v71
	v_exp_f32_e32 v206, v2
	v_fma_f32 v2, v63, s90, -v71
	v_exp_f32_e32 v207, v2
	v_fma_f32 v2, v64, s90, -v71
	s_waitcnt vmcnt(0)
	v_exp_f32_e32 v208, v2
	ds_read_b64_tr_b16 v[2:3], v92
	ds_read_b64_tr_b16 v[4:5], v92 offset:2048
	v_fma_f32 v6, v65, s90, -v71
	v_exp_f32_e32 v209, v6
	v_cvt_pk_bf16_f32 v6, v16, v17
	v_cvt_pk_bf16_f32 v7, v18, v66
	v_cvt_pk_bf16_f32 v8, v67, v68
	v_cvt_pk_bf16_f32 v9, v89, v90
	ds_read_b64_tr_b16 v[10:11], v92 offset:4096
	ds_read_b64_tr_b16 v[12:13], v92 offset:6144
	s_waitcnt lgkmcnt(2)
	v_mfma_f32_32x32x16_bf16 v[50:65], v[2:5], v[6:9], 0
	ds_read_b64_tr_b16 v[2:3], v88
	ds_read_b64_tr_b16 v[4:5], v88 offset:2048
	v_fma_f32 v15, v31, s90, -v71
	v_cvt_pk_bf16_f32 v198, v195, v197
	v_cvt_pk_bf16_f32 v199, v202, v203
	v_cvt_pk_bf16_f32 v200, v206, v207
	v_cvt_pk_bf16_f32 v201, v208, v209
	v_exp_f32_e32 v192, v15
	s_waitcnt lgkmcnt(0)
	v_mfma_f32_32x32x16_bf16 v[34:49], v[2:5], v[6:9], 0
	v_fma_f32 v2, v32, s90, -v71
	v_exp_f32_e32 v193, v2
	v_fma_f32 v2, v33, s90, -v71
	v_exp_f32_e32 v194, v2
	s_andn2_b64 vcc, exec, s[92:93]
	v_mfma_f32_32x32x16_bf16 v[50:65], v[10:13], v[198:201], v[50:65]
	v_add_f32_e32 v10, v189, v14
	v_add_f32_e32 v10, v190, v10
	v_add_f32_e32 v10, v191, v10
	v_add_f32_e32 v14, v192, v10
	ds_read_b64_tr_b16 v[10:11], v88 offset:4096
	ds_read_b64_tr_b16 v[12:13], v88 offset:6144
	ds_read_b64_tr_b16 v[2:3], v93
	ds_read_b64_tr_b16 v[4:5], v93 offset:2048
	s_waitcnt lgkmcnt(2)
	v_mfma_f32_32x32x16_bf16 v[34:49], v[10:13], v[198:201], v[34:49]
	v_add_f32_e32 v10, v193, v14
	v_add_f32_e32 v10, v194, v10
	v_add_f32_e32 v10, v16, v10
	v_add_f32_e32 v10, v17, v10
	v_add_f32_e32 v14, v18, v10
	ds_read_b64_tr_b16 v[10:11], v93 offset:4096
	ds_read_b64_tr_b16 v[12:13], v93 offset:6144
	s_waitcnt lgkmcnt(2)
	v_mfma_f32_32x32x16_bf16 v[18:33], v[2:5], v[6:9], 0
	v_add_f32_e32 v2, v66, v14
	v_add_f32_e32 v2, v67, v2
	v_add_f32_e32 v2, v68, v2
	v_add_f32_e32 v14, v89, v2
	ds_read_b64_tr_b16 v[2:3], v127
	ds_read_b64_tr_b16 v[4:5], v127 offset:2048
	v_or_b32_e32 v68, s79, v1
	s_waitcnt lgkmcnt(2)
	v_mfma_f32_32x32x16_bf16 v[18:33], v[10:13], v[198:201], v[18:33]
	v_add_f32_e32 v10, v90, v14
	v_add_f32_e32 v10, v195, v10
	v_add_f32_e32 v10, v197, v10
	v_add_f32_e32 v10, v202, v10
	v_add_f32_e32 v66, v203, v10
	ds_read_b64_tr_b16 v[202:203], v127 offset:4096
	ds_read_b64_tr_b16 v[204:205], v127 offset:6144
	v_add_f32_e32 v66, v206, v66
	s_waitcnt lgkmcnt(2)
	v_mfma_f32_32x32x16_bf16 v[2:17], v[2:5], v[6:9], 0
	v_add_f32_e32 v66, v207, v66
	v_add_f32_e32 v66, v208, v66
	v_add_f32_e32 v89, v209, v66
	ds_bpermute_b32 v90, v69, v89
	s_waitcnt lgkmcnt(0)
	v_cndmask_b32_e64 v69, 0, 1, s[92:93]
	v_lshl_add_u64 v[66:67], s[8:9], 0, v[94:95]
	s_waitcnt lgkmcnt(1)
	v_mfma_f32_32x32x16_bf16 v[2:17], v[202:205], v[198:201], v[2:17]
	v_cmp_ne_u32_e64 s[8:9], 1, v69
	s_cbranch_vccnz .LBB0_235
	v_ashrrev_i32_e32 v69, 31, v68
	v_lshlrev_b64 v[94:95], 8, v[68:69]
	v_lshl_add_u64 v[94:95], v[66:67], 0, v[94:95]
	s_mov_b64 s[92:93], 0x4000
	v_lshl_add_u64 v[198:199], v[94:95], 0, s[92:93]
	s_mov_b32 s24, m0
	s_mov_b32 m0, s15
	s_nop 0
	global_load_lds_dwordx4 v[198:199], off
	s_mov_b32 m0, s24
	s_mov_b64 s[92:93], 0x4400
	v_lshl_add_u64 v[198:199], v[94:95], 0, s[92:93]
	s_mov_b32 s24, m0
	s_mov_b32 m0, s91
	s_nop 0
	global_load_lds_dwordx4 v[198:199], off
	s_mov_b32 m0, s24
	s_mov_b64 s[92:93], 0x4800
	v_lshl_add_u64 v[198:199], v[94:95], 0, s[92:93]
	s_mov_b32 s24, m0
	s_mov_b32 m0, s26
	s_nop 0
	global_load_lds_dwordx4 v[198:199], off
	s_mov_b32 m0, s24
	s_mov_b64 s[92:93], 0x4c00
	v_lshl_add_u64 v[198:199], v[94:95], 0, s[92:93]
	s_mov_b32 s24, m0
	s_mov_b32 m0, s27
	s_nop 0
	global_load_lds_dwordx4 v[198:199], off
	s_mov_b32 m0, s24
	s_mov_b64 s[92:93], 0x5000
	v_lshl_add_u64 v[198:199], v[94:95], 0, s[92:93]
	s_mov_b32 s24, m0
	s_mov_b32 m0, s28
	s_nop 0
	global_load_lds_dwordx4 v[198:199], off
	s_mov_b32 m0, s24
	s_mov_b64 s[92:93], 0x5400
	v_lshl_add_u64 v[198:199], v[94:95], 0, s[92:93]
	s_mov_b32 s24, m0
	s_mov_b32 m0, s29
	s_nop 0
	global_load_lds_dwordx4 v[198:199], off
	s_mov_b32 m0, s24
	s_mov_b64 s[92:93], 0x5800
	v_lshl_add_u64 v[198:199], v[94:95], 0, s[92:93]
	s_mov_b32 s24, m0
	s_mov_b32 m0, s30
	s_nop 0
	global_load_lds_dwordx4 v[198:199], off
	s_mov_b32 m0, s24
	s_mov_b64 s[92:93], 0x5c00
	v_lshl_add_u64 v[94:95], v[94:95], 0, s[92:93]
	s_mov_b32 s24, m0
	s_mov_b32 m0, s31
	s_nop 0
	global_load_lds_dwordx4 v[94:95], off
	s_mov_b32 m0, s24

.LBB0_259:
	v_cndmask_b32_e64 v3, 0, 1, s[92:93]
	v_mov_b32_e32 v2, 0xff800000
	v_cmp_ne_u32_e64 s[6:7], 1, v3
	s_andn2_b64 vcc, exec, s[92:93]
	v_add_u32_e32 v162, v152, v119
	v_add_u32_e32 v163, v152, v121
	v_add_u32_e32 v158, v152, v142
	v_add_u32_e32 v159, v152, v143
	v_add_u32_e32 v160, v152, v144
	v_add_u32_e32 v161, v152, v145
	v_add_u32_e32 v141, v152, v146
	v_add_u32_e32 v140, v152, v147
	v_mov_b32_e32 v165, 0xff800000
	v_mov_b32_e32 v168, 0xff800000
	v_mov_b32_e32 v164, 0xff800000
	v_mov_b32_e32 v166, 0xff800000
	v_mov_b32_e32 v169, 0xff800000
	v_mov_b32_e32 v172, 0xff800000
	v_mov_b32_e32 v167, 0xff800000
	v_mov_b32_e32 v170, 0xff800000
	v_mov_b32_e32 v173, 0xff800000
	v_mov_b32_e32 v176, 0xff800000
	v_mov_b32_e32 v171, 0xff800000
	v_mov_b32_e32 v174, 0xff800000
	v_mov_b32_e32 v177, 0xff800000
	v_mov_b32_e32 v179, 0xff800000
	v_mov_b32_e32 v175, 0xff800000
	v_mov_b32_e32 v178, 0xff800000
	s_cbranch_vccnz .LBB0_261
	s_sub_i32 s79, s11, 64
	v_or_b32_e32 v8, s79, v1
	v_mov_b32_e32 v9, v105
	v_lshlrev_b64 v[8:9], 8, v[8:9]
	s_waitcnt vmcnt(8)
	v_lshl_add_u64 v[8:9], s[96:97], 0, v[8:9]
	ds_read_b128 v[4:7], v162
	ds_read_b128 v[44:47], v163
	ds_read_b128 v[40:43], v158
	ds_read_b128 v[36:39], v159
	ds_read_b128 v[32:35], v160
	ds_read_b128 v[28:31], v161
	ds_read_b128 v[24:27], v141
	ds_read_b128 v[20:23], v140
	s_waitcnt lgkmcnt(0)
	v_lshl_add_u64 v[8:9], v[8:9], 0, v[104:105]
	s_mov_b32 s92, m0
	s_mov_b32 m0, s15
	s_nop 0
	global_load_lds_dwordx4 v[8:9], off
	s_mov_b32 m0, s92
	v_or_b32_e32 v8, s79, v103
	v_mov_b32_e32 v9, v105
	v_lshlrev_b64 v[8:9], 8, v[8:9]
	v_lshl_add_u64 v[8:9], s[96:97], 0, v[8:9]
	v_mov_b32_e32 v137, v105
	v_lshl_add_u64 v[8:9], v[8:9], 0, v[136:137]
	s_mov_b32 s92, m0
	s_mov_b32 m0, s91
	s_nop 0
	global_load_lds_dwordx4 v[8:9], off
	s_mov_b32 m0, s92
	v_or_b32_e32 v8, s79, v107
	v_mov_b32_e32 v9, v105
	v_lshlrev_b64 v[8:9], 8, v[8:9]
	v_lshl_add_u64 v[8:9], s[96:97], 0, v[8:9]
	v_mov_b32_e32 v135, v105
	v_lshl_add_u64 v[8:9], v[8:9], 0, v[134:135]
	s_mov_b32 s92, m0
	s_mov_b32 m0, s26
	s_nop 0
	global_load_lds_dwordx4 v[8:9], off
	s_mov_b32 m0, s92
	v_or_b32_e32 v8, s79, v109
	v_mov_b32_e32 v9, v105
	v_lshlrev_b64 v[8:9], 8, v[8:9]
	v_lshl_add_u64 v[8:9], s[96:97], 0, v[8:9]
	v_mov_b32_e32 v133, v105
	v_lshl_add_u64 v[8:9], v[8:9], 0, v[132:133]
	s_mov_b32 s92, m0
	s_mov_b32 m0, s27
	s_nop 0
	global_load_lds_dwordx4 v[8:9], off
	s_mov_b32 m0, s92
	v_or_b32_e32 v8, s79, v111
	v_mov_b32_e32 v9, v105
	v_lshlrev_b64 v[8:9], 8, v[8:9]
	v_lshl_add_u64 v[8:9], s[96:97], 0, v[8:9]
	v_lshl_add_u64 v[8:9], v[8:9], 0, v[104:105]
	s_mov_b32 s92, m0
	s_mov_b32 m0, s28
	s_nop 0
	global_load_lds_dwordx4 v[8:9], off
	s_mov_b32 m0, s92
	v_or_b32_e32 v8, s79, v113
	v_mov_b32_e32 v9, v105
	v_lshlrev_b64 v[8:9], 8, v[8:9]
	v_lshl_add_u64 v[8:9], s[96:97], 0, v[8:9]
	v_mov_b32_e32 v131, v105
	v_lshl_add_u64 v[8:9], v[8:9], 0, v[130:131]
	s_mov_b32 s92, m0
	s_mov_b32 m0, s29
	s_nop 0
	global_load_lds_dwordx4 v[8:9], off
	s_mov_b32 m0, s92
	v_or_b32_e32 v8, s79, v115
	v_mov_b32_e32 v9, v105
	v_lshlrev_b64 v[8:9], 8, v[8:9]
	v_lshl_add_u64 v[8:9], s[96:97], 0, v[8:9]
	v_mov_b32_e32 v129, v105
	v_lshl_add_u64 v[8:9], v[8:9], 0, v[128:129]
	s_mov_b32 s92, m0
	s_mov_b32 m0, s30
	s_nop 0
	global_load_lds_dwordx4 v[8:9], off
	s_mov_b32 m0, s92
	v_or_b32_e32 v8, s79, v117
	v_mov_b32_e32 v9, v105
	v_lshlrev_b64 v[8:9], 8, v[8:9]
	v_lshl_add_u64 v[8:9], s[96:97], 0, v[8:9]
	v_mov_b32_e32 v127, v105
	v_lshl_add_u64 v[8:9], v[8:9], 0, v[126:127]
	s_mov_b32 s79, m0
	s_mov_b32 m0, s31
	s_nop 0
	global_load_lds_dwordx4 v[8:9], off
	s_mov_b32 m0, s79
	s_waitcnt lgkmcnt(0)
	v_mfma_f32_32x32x16_bf16 v[4:19], v[4:7], v[50:53], 0
	v_readlane_b32 s92, v242, 2
	v_readlane_b32 s93, v242, 3
	v_mfma_f32_32x32x16_bf16 v[4:19], v[44:47], v[90:93], v[4:19]
	v_mfma_f32_32x32x16_bf16 v[4:19], v[40:43], v[86:89], v[4:19]
	v_mfma_f32_32x32x16_bf16 v[4:19], v[36:39], v[82:85], v[4:19]
	v_mfma_f32_32x32x16_bf16 v[4:19], v[32:35], v[78:81], v[4:19]
	v_mfma_f32_32x32x16_bf16 v[4:19], v[28:31], v[74:77], v[4:19]
	v_mfma_f32_32x32x16_bf16 v[4:19], v[24:27], v[70:73], v[4:19]
	v_mfma_f32_32x32x16_bf16 v[4:19], v[20:23], v[66:69], v[4:19]
	s_nop 11
	v_cndmask_b32_e64 v165, v4, v154, s[92:93]
	v_readlane_b32 s92, v242, 4
	v_readlane_b32 s93, v242, 5
	s_nop 1
	v_cndmask_b32_e64 v168, v5, v154, s[92:93]
	v_readlane_b32 s92, v242, 6
	v_readlane_b32 s93, v242, 7
	s_nop 1
	v_cndmask_b32_e64 v164, v6, v154, s[92:93]
	v_readlane_b32 s92, v242, 8
	v_readlane_b32 s93, v242, 9
	s_nop 1
	v_cndmask_b32_e64 v166, v7, v154, s[92:93]
	v_readlane_b32 s92, v242, 10
	v_readlane_b32 s93, v242, 11
	s_nop 1
	v_cndmask_b32_e64 v169, v8, v154, s[92:93]
	v_readlane_b32 s92, v242, 12
	v_readlane_b32 s93, v242, 13
	s_nop 1
	v_cndmask_b32_e64 v172, v9, v154, s[92:93]
	v_readlane_b32 s92, v242, 14
	v_readlane_b32 s93, v242, 15
	s_nop 1
	v_cndmask_b32_e64 v167, v10, v154, s[92:93]
	v_readlane_b32 s92, v242, 16
	v_readlane_b32 s93, v242, 17
	s_nop 1
	v_cndmask_b32_e64 v170, v11, v154, s[92:93]
	v_readlane_b32 s92, v242, 18
	v_readlane_b32 s93, v242, 19
	s_nop 1
	v_cndmask_b32_e64 v173, v12, v154, s[92:93]
	v_readlane_b32 s92, v242, 20
	v_readlane_b32 s93, v242, 21
	s_nop 1
	v_cndmask_b32_e64 v176, v13, v154, s[92:93]
	v_readlane_b32 s92, v242, 22
	v_readlane_b32 s93, v242, 23
	s_nop 1
	v_cndmask_b32_e64 v171, v14, v154, s[92:93]
	v_readlane_b32 s92, v242, 24
	v_readlane_b32 s93, v242, 25
	s_nop 1
	v_cndmask_b32_e64 v174, v15, v154, s[92:93]
	v_readlane_b32 s92, v242, 26
	v_readlane_b32 s93, v242, 27
	s_nop 1
	v_cndmask_b32_e64 v177, v16, v154, s[92:93]
	v_readlane_b32 s92, v242, 28
	v_readlane_b32 s93, v242, 29
	s_nop 1
	v_cndmask_b32_e64 v179, v17, v154, s[92:93]
	v_readlane_b32 s92, v242, 30
	v_readlane_b32 s93, v242, 31
	s_nop 1
	v_cndmask_b32_e64 v175, v18, v154, s[92:93]
	v_readlane_b32 s92, v242, 32
	v_readlane_b32 s93, v242, 33
	s_nop 1
	v_cndmask_b32_e64 v178, v19, v154, s[92:93]
.LBB0_261:
	s_cmpk_gt_u32 s24, 0x5f
	s_cselect_b64 s[92:93], -1, 0
	s_cmpk_lt_u32 s24, 0x60
	v_mov_b32_e32 v3, 0xff800000
	v_mov_b32_e32 v4, 0xff800000
	v_mov_b32_e32 v5, 0xff800000
	v_mov_b32_e32 v6, 0xff800000
	v_mov_b32_e32 v7, 0xff800000
	v_mov_b32_e32 v8, 0xff800000
	v_mov_b32_e32 v9, 0xff800000
	v_mov_b32_e32 v10, 0xff800000
	v_mov_b32_e32 v11, 0xff800000
	v_mov_b32_e32 v12, 0xff800000
	v_mov_b32_e32 v13, 0xff800000
	v_mov_b32_e32 v14, 0xff800000
	v_mov_b32_e32 v15, 0xff800000
	v_mov_b32_e32 v16, 0xff800000
	v_mov_b32_e32 v17, 0xff800000
	s_cbranch_scc1 .LBB0_263
	s_sub_i32 s79, s11, 32
	v_or_b32_e32 v6, s79, v1
	v_mov_b32_e32 v7, v105
	v_lshlrev_b64 v[6:7], 8, v[6:7]
	s_waitcnt vmcnt(8)
	v_lshl_add_u64 v[6:7], s[96:97], 0, v[6:7]
	ds_read_b128 v[2:5], v162 offset:8192
	ds_read_b128 v[42:45], v163 offset:8192
	ds_read_b128 v[38:41], v158 offset:8192
	ds_read_b128 v[34:37], v159 offset:8192
	ds_read_b128 v[30:33], v160 offset:8192
	ds_read_b128 v[26:29], v161 offset:8192
	ds_read_b128 v[22:25], v141 offset:8192
	ds_read_b128 v[18:21], v140 offset:8192
	s_waitcnt lgkmcnt(0)
	v_lshl_add_u64 v[6:7], v[6:7], 0, v[104:105]
	s_mov_b32 s94, m0
	s_mov_b32 m0, s33
	s_nop 0
	global_load_lds_dwordx4 v[6:7], off
	s_mov_b32 m0, s94
	v_or_b32_e32 v6, s79, v103
	v_mov_b32_e32 v7, v105
	v_lshlrev_b64 v[6:7], 8, v[6:7]
	v_lshl_add_u64 v[6:7], s[96:97], 0, v[6:7]
	v_mov_b32_e32 v137, v105
	v_lshl_add_u64 v[6:7], v[6:7], 0, v[136:137]
	s_mov_b32 s94, m0
	s_mov_b32 m0, s34
	s_nop 0
	global_load_lds_dwordx4 v[6:7], off
	s_mov_b32 m0, s94
	v_or_b32_e32 v6, s79, v107
	v_mov_b32_e32 v7, v105
	v_lshlrev_b64 v[6:7], 8, v[6:7]
	v_lshl_add_u64 v[6:7], s[96:97], 0, v[6:7]
	v_mov_b32_e32 v135, v105
	v_lshl_add_u64 v[6:7], v[6:7], 0, v[134:135]
	s_mov_b32 s94, m0
	s_mov_b32 m0, s35
	s_nop 0
	global_load_lds_dwordx4 v[6:7], off
	s_mov_b32 m0, s94
	v_or_b32_e32 v6, s79, v109
	v_mov_b32_e32 v7, v105
	v_lshlrev_b64 v[6:7], 8, v[6:7]
	v_lshl_add_u64 v[6:7], s[96:97], 0, v[6:7]
	v_mov_b32_e32 v133, v105
	v_lshl_add_u64 v[6:7], v[6:7], 0, v[132:133]
	s_mov_b32 s94, m0
	s_mov_b32 m0, s36
	s_nop 0
	global_load_lds_dwordx4 v[6:7], off
	s_mov_b32 m0, s94
	v_or_b32_e32 v6, s79, v111
	v_mov_b32_e32 v7, v105
	v_lshlrev_b64 v[6:7], 8, v[6:7]
	v_lshl_add_u64 v[6:7], s[96:97], 0, v[6:7]
	v_lshl_add_u64 v[6:7], v[6:7], 0, v[104:105]
	s_mov_b32 s94, m0
	s_mov_b32 m0, s37
	s_nop 0
	global_load_lds_dwordx4 v[6:7], off
	s_mov_b32 m0, s94
	v_or_b32_e32 v6, s79, v113
	v_mov_b32_e32 v7, v105
	v_lshlrev_b64 v[6:7], 8, v[6:7]
	v_lshl_add_u64 v[6:7], s[96:97], 0, v[6:7]
	v_mov_b32_e32 v131, v105
	v_lshl_add_u64 v[6:7], v[6:7], 0, v[130:131]
	s_mov_b32 s94, m0
	s_mov_b32 m0, s16
	s_nop 0
	global_load_lds_dwordx4 v[6:7], off
	s_mov_b32 m0, s94
	v_or_b32_e32 v6, s79, v115
	v_mov_b32_e32 v7, v105
	v_lshlrev_b64 v[6:7], 8, v[6:7]
	v_lshl_add_u64 v[6:7], s[96:97], 0, v[6:7]
	v_mov_b32_e32 v129, v105
	v_lshl_add_u64 v[6:7], v[6:7], 0, v[128:129]
	s_mov_b32 s94, m0
	s_mov_b32 m0, s17
	s_nop 0
	global_load_lds_dwordx4 v[6:7], off
	s_mov_b32 m0, s94
	v_or_b32_e32 v6, s79, v117
	v_mov_b32_e32 v7, v105
	v_lshlrev_b64 v[6:7], 8, v[6:7]
	v_lshl_add_u64 v[6:7], s[96:97], 0, v[6:7]
	v_mov_b32_e32 v127, v105
	v_lshl_add_u64 v[6:7], v[6:7], 0, v[126:127]
	s_mov_b32 s79, m0
	s_mov_b32 m0, s13
	s_nop 0
	global_load_lds_dwordx4 v[6:7], off
	s_mov_b32 m0, s79
	s_waitcnt lgkmcnt(0)
	v_mfma_f32_32x32x16_bf16 v[2:17], v[2:5], v[50:53], 0
	v_mfma_f32_32x32x16_bf16 v[2:17], v[42:45], v[90:93], v[2:17]
	v_mfma_f32_32x32x16_bf16 v[2:17], v[38:41], v[86:89], v[2:17]
	v_mfma_f32_32x32x16_bf16 v[2:17], v[34:37], v[82:85], v[2:17]
	v_mfma_f32_32x32x16_bf16 v[2:17], v[30:33], v[78:81], v[2:17]
	v_mfma_f32_32x32x16_bf16 v[2:17], v[26:29], v[74:77], v[2:17]
	v_mfma_f32_32x32x16_bf16 v[2:17], v[22:25], v[70:73], v[2:17]
	v_mfma_f32_32x32x16_bf16 v[2:17], v[18:21], v[66:69], v[2:17]
.LBB0_263:
	v_or_b32_e32 v19, s11, v1
	s_cmp_gt_u32 s24, 63
	v_mov_b32_e32 v18, 0xff800000
	s_cselect_b64 s[94:95], -1, 0
	s_cmp_lt_u32 s24, 64
	v_lshlrev_b32_e32 v138, 8, v19
	v_mov_b32_e32 v34, 0xff800000
	v_mov_b32_e32 v35, 0xff800000
	v_mov_b32_e32 v36, 0xff800000
	v_mov_b32_e32 v37, 0xff800000
	v_mov_b32_e32 v38, 0xff800000
	v_mov_b32_e32 v39, 0xff800000
	v_mov_b32_e32 v40, 0xff800000
	v_mov_b32_e32 v41, 0xff800000
	v_mov_b32_e32 v42, 0xff800000
	v_mov_b32_e32 v43, 0xff800000
	v_mov_b32_e32 v44, 0xff800000
	v_mov_b32_e32 v45, 0xff800000
	v_mov_b32_e32 v46, 0xff800000
	v_mov_b32_e32 v47, 0xff800000
	v_mov_b32_e32 v48, 0xff800000
	v_mov_b32_e32 v49, 0xff800000
	s_cbranch_scc1 .LBB0_265
	v_mov_b32_e32 v139, v105
	s_waitcnt vmcnt(8)
	v_lshl_add_u64 v[36:37], s[96:97], 0, v[138:139]
	ds_read_b128 v[32:35], v162
	ds_read_b128 v[94:97], v163
	ds_read_b128 v[62:65], v158
	ds_read_b128 v[58:61], v159
	ds_read_b128 v[54:57], v160
	ds_read_b128 v[28:31], v161
	ds_read_b128 v[24:27], v141
	ds_read_b128 v[20:23], v140
	s_waitcnt lgkmcnt(0)
	v_lshl_add_u64 v[36:37], v[36:37], 0, v[104:105]
	v_or_b32_e32 v19, s11, v103
	s_mov_b32 s79, m0
	s_mov_b32 m0, s15
	s_nop 0
	global_load_lds_dwordx4 v[36:37], off
	s_mov_b32 m0, s79
	v_lshlrev_b32_e32 v36, 8, v19
	v_mov_b32_e32 v37, v105
	v_lshl_add_u64 v[36:37], s[96:97], 0, v[36:37]
	v_mov_b32_e32 v137, v105
	v_lshl_add_u64 v[36:37], v[36:37], 0, v[136:137]
	v_or_b32_e32 v19, s11, v107
	s_mov_b32 s79, m0
	s_mov_b32 m0, s91
	s_nop 0
	global_load_lds_dwordx4 v[36:37], off
	s_mov_b32 m0, s79
	v_lshlrev_b32_e32 v36, 8, v19
	v_mov_b32_e32 v37, v105
	v_lshl_add_u64 v[36:37], s[96:97], 0, v[36:37]
	v_mov_b32_e32 v135, v105
	v_lshl_add_u64 v[36:37], v[36:37], 0, v[134:135]
	v_or_b32_e32 v19, s11, v109
	s_mov_b32 s79, m0
	s_mov_b32 m0, s26
	s_nop 0
	global_load_lds_dwordx4 v[36:37], off
	s_mov_b32 m0, s79
	v_lshlrev_b32_e32 v36, 8, v19
	v_mov_b32_e32 v37, v105
	v_lshl_add_u64 v[36:37], s[96:97], 0, v[36:37]
	v_mov_b32_e32 v133, v105
	v_lshl_add_u64 v[36:37], v[36:37], 0, v[132:133]
	v_or_b32_e32 v19, s11, v111
	s_mov_b32 s79, m0
	s_mov_b32 m0, s27
	s_nop 0
	global_load_lds_dwordx4 v[36:37], off
	s_mov_b32 m0, s79
	v_lshlrev_b32_e32 v36, 8, v19
	v_mov_b32_e32 v37, v105
	v_lshl_add_u64 v[36:37], s[96:97], 0, v[36:37]
	v_or_b32_e32 v19, s11, v113
	v_lshl_add_u64 v[36:37], v[36:37], 0, v[104:105]
	v_lshlrev_b32_e32 v104, 8, v19
	s_mov_b32 s79, m0
	s_mov_b32 m0, s28
	s_nop 0
	global_load_lds_dwordx4 v[36:37], off
	s_mov_b32 m0, s79
	v_lshl_add_u64 v[36:37], s[96:97], 0, v[104:105]
	v_mov_b32_e32 v131, v105
	v_or_b32_e32 v19, s11, v115
	v_lshl_add_u64 v[36:37], v[36:37], 0, v[130:131]
	v_lshlrev_b32_e32 v104, 8, v19
	s_mov_b32 s79, m0
	s_mov_b32 m0, s29
	s_nop 0
	global_load_lds_dwordx4 v[36:37], off
	s_mov_b32 m0, s79
	v_lshl_add_u64 v[36:37], s[96:97], 0, v[104:105]
	v_mov_b32_e32 v129, v105
	v_or_b32_e32 v19, s11, v117
	v_lshl_add_u64 v[36:37], v[36:37], 0, v[128:129]
	v_lshlrev_b32_e32 v104, 8, v19
	s_mov_b32 s79, m0
	s_mov_b32 m0, s30
	s_nop 0
	global_load_lds_dwordx4 v[36:37], off
	s_mov_b32 m0, s79
	v_lshl_add_u64 v[36:37], s[96:97], 0, v[104:105]
	v_mov_b32_e32 v127, v105
	v_lshl_add_u64 v[36:37], v[36:37], 0, v[126:127]
	s_mov_b32 s79, m0
	s_mov_b32 m0, s31
	s_nop 0
	global_load_lds_dwordx4 v[36:37], off
	s_mov_b32 m0, s79
	s_waitcnt lgkmcnt(0)
	v_mfma_f32_32x32x16_bf16 v[34:49], v[32:35], v[50:53], 0
	v_mfma_f32_32x32x16_bf16 v[34:49], v[94:97], v[90:93], v[34:49]
	v_mfma_f32_32x32x16_bf16 v[34:49], v[62:65], v[86:89], v[34:49]
	v_mfma_f32_32x32x16_bf16 v[34:49], v[58:61], v[82:85], v[34:49]
	v_mfma_f32_32x32x16_bf16 v[34:49], v[54:57], v[78:81], v[34:49]
	v_mfma_f32_32x32x16_bf16 v[34:49], v[28:31], v[74:77], v[34:49]
	v_mfma_f32_32x32x16_bf16 v[34:49], v[24:27], v[70:73], v[34:49]
	v_mfma_f32_32x32x16_bf16 v[34:49], v[20:23], v[66:69], v[34:49]
.LBB0_265:
	s_lshl_b64 s[8:9], s[8:9], 19
	s_lshl_b64 s[8:9], s[8:9], 1
	v_readlane_b32 s79, v243, 20
	s_add_u32 s8, s79, s8
	v_readlane_b32 s79, v243, 21
	s_addc_u32 s9, s79, s9
	s_cmp_lg_u32 s24, 0
	s_cselect_b64 s[96:97], -1, 0
	s_cmp_eq_u32 s24, 0
	v_lshlrev_b32_e32 v104, 1, v120
	v_mov_b32_e32 v19, 0xff800000
	v_mov_b32_e32 v20, 0xff800000
	v_mov_b32_e32 v21, 0xff800000
	v_mov_b32_e32 v22, 0xff800000
	v_mov_b32_e32 v23, 0xff800000
	v_mov_b32_e32 v24, 0xff800000
	v_mov_b32_e32 v25, 0xff800000
	v_mov_b32_e32 v26, 0xff800000
	v_mov_b32_e32 v27, 0xff800000
	v_mov_b32_e32 v28, 0xff800000
	v_mov_b32_e32 v29, 0xff800000
	v_mov_b32_e32 v30, 0xff800000
	v_mov_b32_e32 v31, 0xff800000
	v_mov_b32_e32 v32, 0xff800000
	v_mov_b32_e32 v33, 0xff800000
	s_cbranch_scc1 .LBB0_267
	s_waitcnt vmcnt(8)
	ds_read_b128 v[18:21], v162 offset:8192
	ds_read_b128 v[54:57], v163 offset:8192
	v_mov_b32_e32 v139, v105
	s_movk_i32 vcc_lo, 0xe000
	s_mov_b32 vcc_hi, -1
	s_waitcnt lgkmcnt(0)
	v_mfma_f32_32x32x16_bf16 v[18:33], v[18:21], v[50:53], 0
	v_mfma_f32_32x32x16_bf16 v[18:33], v[54:57], v[90:93], v[18:33]
	ds_read_b128 v[54:57], v158 offset:8192
	ds_read_b128 v[58:61], v159 offset:8192
	s_waitcnt lgkmcnt(1)
	v_mfma_f32_32x32x16_bf16 v[18:33], v[54:57], v[86:89], v[18:33]
	ds_read_b128 v[54:57], v160 offset:8192
	s_waitcnt lgkmcnt(1)
	v_mfma_f32_32x32x16_bf16 v[18:33], v[58:61], v[82:85], v[18:33]
	ds_read_b128 v[58:61], v161 offset:8192
	s_waitcnt lgkmcnt(1)
	v_mfma_f32_32x32x16_bf16 v[18:33], v[54:57], v[78:81], v[18:33]
	v_lshl_add_u64 v[54:55], s[8:9], 0, v[138:139]
	v_lshl_add_u64 v[94:95], v[54:55], 0, v[104:105]
	ds_read_b128 v[54:57], v141 offset:8192
	ds_read_b128 v[62:65], v140 offset:8192
	v_lshl_add_u64 v[96:97], v[94:95], 0, vcc
	s_movk_i32 vcc_lo, 0xe400
	s_mov_b32 vcc_hi, -1
	s_waitcnt lgkmcnt(0)
	s_waitcnt lgkmcnt(2)
	v_mfma_f32_32x32x16_bf16 v[18:33], v[58:61], v[74:77], v[18:33]
	v_lshl_add_u64 v[58:59], v[94:95], 0, vcc
	s_movk_i32 vcc_lo, 0xe800
	s_mov_b32 s79, m0
	s_mov_b32 m0, s33
	s_nop 0
	global_load_lds_dwordx4 v[96:97], off
	s_mov_b32 m0, s79
	s_mov_b32 vcc_hi, -1
	s_mov_b32 s79, m0
	s_mov_b32 m0, s34
	s_nop 0
	global_load_lds_dwordx4 v[58:59], off
	s_mov_b32 m0, s79
	v_lshl_add_u64 v[58:59], v[94:95], 0, vcc
	s_movk_i32 vcc_lo, 0xec00
	s_waitcnt lgkmcnt(1)
	v_mfma_f32_32x32x16_bf16 v[18:33], v[54:57], v[70:73], v[18:33]
	s_mov_b32 vcc_hi, -1
	s_mov_b32 s79, m0
	s_mov_b32 m0, s35
	s_nop 0
	global_load_lds_dwordx4 v[58:59], off
	s_mov_b32 m0, s79
	v_lshl_add_u64 v[58:59], v[94:95], 0, vcc
	s_movk_i32 vcc_lo, 0xf000
	s_mov_b32 vcc_hi, -1
	s_mov_b32 s79, m0
	s_mov_b32 m0, s36
	s_nop 0
	global_load_lds_dwordx4 v[58:59], off
	s_mov_b32 m0, s79
	v_lshl_add_u64 v[58:59], v[94:95], 0, vcc
	s_movk_i32 vcc_lo, 0xf400
	s_mov_b32 vcc_hi, -1
	s_waitcnt lgkmcnt(0)
	v_mfma_f32_32x32x16_bf16 v[18:33], v[62:65], v[66:69], v[18:33]
	v_lshl_add_u64 v[54:55], v[94:95], 0, vcc
	s_movk_i32 vcc_lo, 0xf800
	s_mov_b32 s79, m0
	s_mov_b32 m0, s37
	s_nop 0
	global_load_lds_dwordx4 v[58:59], off
	s_mov_b32 m0, s79
	s_mov_b32 vcc_hi, -1
	s_mov_b32 s79, m0
	s_mov_b32 m0, s16
	s_nop 0
	global_load_lds_dwordx4 v[54:55], off
	s_mov_b32 m0, s79
	v_lshl_add_u64 v[54:55], v[94:95], 0, vcc
	s_movk_i32 vcc_lo, 0xfc00
	s_mov_b32 s79, m0
	s_mov_b32 m0, s17
	s_nop 0
	global_load_lds_dwordx4 v[54:55], off
	s_mov_b32 m0, s79
	s_mov_b32 vcc_hi, -1
	v_lshl_add_u64 v[54:55], v[94:95], 0, vcc
	s_mov_b32 s79, m0
	s_mov_b32 m0, s13
	s_nop 0
	global_load_lds_dwordx4 v[54:55], off
	s_mov_b32 m0, s79

.LBB0_270:
	ds_read_b128 v[54:57], v162
	ds_read_b128 v[94:97], v163
	ds_read_b128 v[126:129], v158
	ds_read_b128 v[130:133], v159
	ds_read_b128 v[134:137], v160
	ds_read_b128 v[158:161], v161
	s_mov_b32 s79, 0xff800000
	v_mov_b32_e32 v139, v105
	s_waitcnt lgkmcnt(0)
	v_mfma_f32_32x32x16_bf16 v[50:65], v[54:57], v[50:53], 0
	v_lshl_add_u64 v[138:139], s[8:9], 0, v[138:139]
	v_lshl_add_u64 v[138:139], v[138:139], 0, v[104:105]
	s_mov_b64 vcc, 0x400
	v_mfma_f32_32x32x16_bf16 v[50:65], v[94:97], v[90:93], v[50:65]
	ds_read_b128 v[90:93], v141
	ds_read_b128 v[94:97], v140
	v_max3_f32 v140, v165, s79, v168
	v_max3_f32 v140, v140, v164, v166
	v_max3_f32 v140, v140, v169, v172
	v_max3_f32 v140, v140, v167, v170
	s_waitcnt lgkmcnt(0)
	s_mov_b32 s79, m0
	s_mov_b32 m0, s15
	s_nop 0
	global_load_lds_dwordx4 v[138:139], off
	s_mov_b32 m0, s79
	v_mfma_f32_32x32x16_bf16 v[50:65], v[126:129], v[86:89], v[50:65]
	v_lshl_add_u64 v[86:87], v[138:139], 0, vcc
	s_mov_b64 vcc, 0x800
	v_lshl_add_u64 v[88:89], v[138:139], 0, vcc
	s_mov_b32 s79, m0
	s_mov_b32 m0, s91
	s_nop 0
	global_load_lds_dwordx4 v[86:87], off
	s_mov_b32 m0, s79
	v_lshl_add_u64 v[126:127], v[138:139], 0, s[80:81]
	s_mov_b32 s79, m0
	s_mov_b32 m0, s26
	s_nop 0
	global_load_lds_dwordx4 v[88:89], off
	s_mov_b32 m0, s79
	v_lshl_add_u64 v[128:129], v[138:139], 0, s[82:83]
	v_mfma_f32_32x32x16_bf16 v[50:65], v[130:133], v[82:85], v[50:65]
	v_max3_f32 v82, v140, v173, v176
	v_max3_f32 v82, v82, v171, v174
	v_max3_f32 v82, v82, v177, v179
	v_max3_f32 v82, v82, v175, v178
	s_mov_b32 s79, m0
	s_mov_b32 m0, s27
	s_nop 0
	global_load_lds_dwordx4 v[126:127], off
	s_mov_b32 m0, s79
	s_nop 0
	s_mov_b32 s79, m0
	s_mov_b32 m0, s28
	s_nop 0
	global_load_lds_dwordx4 v[128:129], off
	s_mov_b32 m0, s79
	v_mfma_f32_32x32x16_bf16 v[50:65], v[134:137], v[78:81], v[50:65]
	v_max3_f32 v78, v82, v2, v3
	v_max3_f32 v78, v78, v4, v5
	v_max3_f32 v78, v78, v6, v7
	v_max3_f32 v78, v78, v8, v9
	v_max3_f32 v78, v78, v10, v11
	v_max3_f32 v78, v78, v12, v13
	v_max3_f32 v78, v78, v14, v15
	v_mfma_f32_32x32x16_bf16 v[50:65], v[158:161], v[74:77], v[50:65]
	v_max3_f32 v74, v78, v16, v17
	v_max3_f32 v74, v74, v34, v35
	v_max3_f32 v74, v74, v36, v37
	v_max3_f32 v74, v74, v38, v39
	v_max3_f32 v74, v74, v40, v41
	v_max3_f32 v74, v74, v42, v43
	v_max3_f32 v74, v74, v44, v45
	s_waitcnt lgkmcnt(1)
	v_mfma_f32_32x32x16_bf16 v[50:65], v[90:93], v[70:73], v[50:65]
	v_max3_f32 v70, v74, v46, v47
	v_max3_f32 v70, v70, v48, v49
	v_max3_f32 v70, v70, v18, v19
	v_max3_f32 v70, v70, v20, v21
	v_max3_f32 v70, v70, v22, v23
	v_max3_f32 v70, v70, v24, v25
	v_max3_f32 v70, v70, v26, v27
	s_waitcnt lgkmcnt(0)
	v_mfma_f32_32x32x16_bf16 v[50:65], v[94:97], v[66:69], v[50:65]
	v_add_u32_e32 v91, v153, v148
	v_add_u32_e32 v92, v153, v150
	v_add_u32_e32 v95, v153, v151
	s_nop 8
	v_cndmask_b32_e64 v66, v50, v154, s[38:39]
	v_cndmask_b32_e64 v69, v52, v154, s[42:43]
	v_cndmask_b32_e64 v52, v65, v154, s[68:69]
	v_cndmask_b32_e64 v65, v66, v50, s[40:41]
	v_max3_f32 v50, v70, v28, v29
	v_max3_f32 v50, v50, v30, v31
	v_cndmask_b32_e64 v68, v154, v51, s[40:41]
	v_max3_f32 v50, v50, v32, v33
	v_cndmask_b32_e64 v71, v53, v154, s[44:45]
	v_max3_f32 v50, v50, v65, v68
	v_cndmask_b32_e64 v54, v54, v154, s[46:47]
	v_cndmask_b32_e64 v55, v55, v154, s[48:49]
	v_max3_f32 v50, v50, v69, v71
	v_cndmask_b32_e64 v56, v56, v154, s[50:51]
	v_cndmask_b32_e64 v57, v57, v154, s[52:53]
	v_max3_f32 v50, v50, v54, v55
	v_cndmask_b32_e64 v58, v58, v154, s[54:55]
	v_cndmask_b32_e64 v59, v59, v154, s[56:57]
	v_max3_f32 v50, v50, v56, v57
	v_cndmask_b32_e64 v60, v60, v154, s[58:59]
	v_cndmask_b32_e64 v61, v61, v154, s[60:61]
	v_max3_f32 v50, v50, v58, v59
	v_cndmask_b32_e64 v62, v62, v154, s[62:63]
	v_cndmask_b32_e64 v63, v63, v154, s[64:65]
	v_max3_f32 v50, v50, v60, v61
	v_cndmask_b32_e64 v64, v64, v154, s[66:67]
	v_max3_f32 v50, v50, v62, v63
	v_and_b32_e32 v51, 64, v155
	v_max3_f32 v53, v50, v64, v52
	v_xor_b32_e32 v50, 32, v155
	v_add_u32_e32 v51, 64, v51
	v_cmp_lt_i32_e32 vcc, v50, v51
	s_nop 1
	v_cndmask_b32_e32 v50, v155, v50, vcc
	v_lshlrev_b32_e32 v70, 2, v50
	ds_bpermute_b32 v66, v70, v53
	v_lshl_add_u64 v[50:51], v[138:139], 0, s[84:85]
	s_mov_b32 s79, m0
	s_mov_b32 m0, s29
	s_nop 0
	global_load_lds_dwordx4 v[50:51], off
	s_mov_b32 m0, s79
	v_lshl_add_u64 v[50:51], v[138:139], 0, s[86:87]
	s_mov_b32 s79, m0
	s_mov_b32 m0, s30
	s_nop 0
	global_load_lds_dwordx4 v[50:51], off
	s_mov_b32 m0, s79
	s_waitcnt lgkmcnt(0)
	v_max_f32_e32 v50, v66, v66
	v_max_f32_e32 v53, v53, v50
	v_pk_mul_f32 v[66:67], v[52:53], s[90:91] op_sel_hi:[1,0]
	s_andn2_b64 vcc, exec, s[94:95]
	v_fma_f32 v50, v165, s90, -v67
	v_exp_f32_e32 v72, v50
	v_fma_f32 v50, v168, s90, -v67
	v_exp_f32_e32 v73, v50
	v_lshl_add_u64 v[50:51], v[138:139], 0, s[88:89]
	s_mov_b32 s79, m0
	s_mov_b32 m0, s31
	s_nop 0
	global_load_lds_dwordx4 v[50:51], off
	s_mov_b32 m0, s79
	v_fma_f32 v51, v164, s90, -v67
	v_exp_f32_e32 v74, v51
	v_fma_f32 v51, v166, s90, -v67
	v_exp_f32_e32 v75, v51
	v_fma_f32 v51, v169, s90, -v67
	v_add_f32_e32 v50, 0, v72
	v_exp_f32_e32 v76, v51
	v_fma_f32 v51, v172, s90, -v67
	v_add_f32_e32 v50, v73, v50
	v_exp_f32_e32 v77, v51
	v_fma_f32 v51, v167, s90, -v67
	v_add_f32_e32 v50, v74, v50
	v_exp_f32_e32 v78, v51
	v_fma_f32 v51, v170, s90, -v67
	v_add_f32_e32 v50, v75, v50
	v_exp_f32_e32 v79, v51
	v_fma_f32 v51, v173, s90, -v67
	v_add_f32_e32 v50, v76, v50
	v_exp_f32_e32 v80, v51
	v_fma_f32 v51, v176, s90, -v67
	v_add_f32_e32 v50, v77, v50
	v_exp_f32_e32 v81, v51
	v_fma_f32 v51, v171, s90, -v67
	v_add_f32_e32 v50, v78, v50
	v_exp_f32_e32 v82, v51
	v_fma_f32 v51, v174, s90, -v67
	v_add_f32_e32 v50, v79, v50
	v_exp_f32_e32 v83, v51
	v_fma_f32 v51, v177, s90, -v67
	v_add_f32_e32 v50, v80, v50
	v_exp_f32_e32 v84, v51
	v_fma_f32 v51, v179, s90, -v67
	v_add_f32_e32 v50, v81, v50
	v_exp_f32_e32 v85, v51
	v_fma_f32 v51, v175, s90, -v67
	v_add_f32_e32 v50, v82, v50
	v_exp_f32_e32 v86, v51
	v_fma_f32 v51, v178, s90, -v67
	v_add_f32_e32 v50, v83, v50
	v_exp_f32_e32 v87, v51
	v_fma_f32 v2, v2, s90, -v67
	v_add_f32_e32 v50, v84, v50
	v_exp_f32_e32 v90, v2
	v_fma_f32 v2, v3, s90, -v67
	v_add_f32_e32 v50, v85, v50
	v_exp_f32_e32 v93, v2
	v_fma_f32 v3, v4, s90, -v67
	v_add_f32_e32 v2, v86, v50
	v_exp_f32_e32 v94, v3
	v_fma_f32 v3, v5, s90, -v67
	v_add_f32_e32 v2, v87, v2
	v_exp_f32_e32 v96, v3
	v_fma_f32 v3, v6, s90, -v67
	v_add_f32_e32 v2, v90, v2
	v_exp_f32_e32 v97, v3
	v_fma_f32 v3, v7, s90, -v67
	v_add_f32_e32 v2, v93, v2
	v_exp_f32_e32 v126, v3
	v_fma_f32 v3, v8, s90, -v67
	v_add_f32_e32 v2, v94, v2
	v_exp_f32_e32 v127, v3
	v_fma_f32 v3, v9, s90, -v67
	v_add_f32_e32 v2, v96, v2
	v_exp_f32_e32 v128, v3
	v_fma_f32 v3, v10, s90, -v67
	v_add_f32_e32 v2, v97, v2
	v_exp_f32_e32 v129, v3
	v_fma_f32 v3, v11, s90, -v67
	v_add_f32_e32 v2, v126, v2
	v_exp_f32_e32 v130, v3
	v_fma_f32 v3, v12, s90, -v67
	v_add_f32_e32 v2, v127, v2
	v_exp_f32_e32 v131, v3
	v_fma_f32 v3, v13, s90, -v67
	v_add_f32_e32 v2, v128, v2
	v_exp_f32_e32 v132, v3
	v_fma_f32 v3, v14, s90, -v67
	v_add_f32_e32 v2, v129, v2
	v_exp_f32_e32 v133, v3
	v_fma_f32 v3, v15, s90, -v67
	v_add_f32_e32 v2, v130, v2
	v_exp_f32_e32 v134, v3
	v_fma_f32 v3, v16, s90, -v67
	v_add_f32_e32 v2, v131, v2
	v_exp_f32_e32 v135, v3
	v_fma_f32 v3, v17, s90, -v67
	v_add_f32_e32 v2, v132, v2
	v_exp_f32_e32 v136, v3
	v_fma_f32 v3, v34, s90, -v67
	v_add_f32_e32 v2, v133, v2
	v_exp_f32_e32 v137, v3
	v_fma_f32 v3, v35, s90, -v67
	v_add_f32_e32 v2, v134, v2
	v_exp_f32_e32 v138, v3
	v_fma_f32 v3, v36, s90, -v67
	v_add_f32_e32 v2, v135, v2
	v_exp_f32_e32 v139, v3
	v_fma_f32 v3, v37, s90, -v67
	v_add_f32_e32 v2, v136, v2
	v_exp_f32_e32 v140, v3
	v_fma_f32 v3, v38, s90, -v67
	v_add_f32_e32 v2, v137, v2
	v_exp_f32_e32 v141, v3
	v_fma_f32 v3, v39, s90, -v67
	v_add_f32_e32 v2, v138, v2
	v_exp_f32_e32 v158, v3
	v_fma_f32 v3, v40, s90, -v67
	v_add_f32_e32 v2, v139, v2
	v_exp_f32_e32 v159, v3
	v_fma_f32 v3, v41, s90, -v67
	v_add_f32_e32 v2, v140, v2
	v_exp_f32_e32 v160, v3
	v_fma_f32 v3, v42, s90, -v67
	v_add_f32_e32 v2, v141, v2
	v_exp_f32_e32 v161, v3
	v_fma_f32 v3, v43, s90, -v67
	v_add_f32_e32 v2, v158, v2
	v_exp_f32_e32 v162, v3
	v_fma_f32 v3, v44, s90, -v67
	v_add_f32_e32 v2, v159, v2
	v_exp_f32_e32 v163, v3
	v_fma_f32 v3, v45, s90, -v67
	v_add_f32_e32 v2, v160, v2
	v_exp_f32_e32 v164, v3
	v_fma_f32 v3, v46, s90, -v67
	v_add_f32_e32 v2, v161, v2
	v_exp_f32_e32 v165, v3
	v_fma_f32 v3, v47, s90, -v67
	v_add_f32_e32 v2, v162, v2
	v_exp_f32_e32 v166, v3
	v_fma_f32 v3, v48, s90, -v67
	v_add_f32_e32 v2, v163, v2
	v_exp_f32_e32 v167, v3
	v_fma_f32 v3, v49, s90, -v67
	v_add_f32_e32 v2, v164, v2
	v_exp_f32_e32 v168, v3
	v_fma_f32 v3, v18, s90, -v67
	v_add_f32_e32 v2, v165, v2
	v_exp_f32_e32 v169, v3
	v_fma_f32 v3, v19, s90, -v67
	v_add_f32_e32 v2, v166, v2
	v_exp_f32_e32 v170, v3
	v_fma_f32 v3, v20, s90, -v67
	v_add_f32_e32 v2, v167, v2
	v_exp_f32_e32 v171, v3
	v_fma_f32 v3, v21, s90, -v67
	v_add_f32_e32 v2, v168, v2
	v_exp_f32_e32 v172, v3
	v_fma_f32 v3, v22, s90, -v67
	v_add_f32_e32 v2, v169, v2
	v_exp_f32_e32 v173, v3
	v_fma_f32 v3, v23, s90, -v67
	v_add_f32_e32 v2, v170, v2
	v_exp_f32_e32 v174, v3
	v_fma_f32 v3, v24, s90, -v67
	v_add_f32_e32 v2, v171, v2
	v_exp_f32_e32 v175, v3
	v_fma_f32 v3, v25, s90, -v67
	v_add_f32_e32 v2, v172, v2
	v_exp_f32_e32 v176, v3
	v_fma_f32 v3, v26, s90, -v67
	v_add_f32_e32 v2, v173, v2
	v_exp_f32_e32 v177, v3
	v_fma_f32 v3, v27, s90, -v67
	v_add_f32_e32 v2, v174, v2
	v_exp_f32_e32 v178, v3
	v_add_f32_e32 v2, v175, v2
	v_add_f32_e32 v2, v176, v2
	v_add_f32_e32 v2, v177, v2
	v_add_f32_e32 v14, v178, v2
	v_fma_f32 v2, v28, s90, -v67
	v_exp_f32_e32 v179, v2
	v_fma_f32 v2, v29, s90, -v67
	v_exp_f32_e32 v180, v2
	v_fma_f32 v2, v30, s90, -v67
	v_exp_f32_e32 v181, v2
	v_fma_f32 v2, v65, s90, -v67
	v_exp_f32_e32 v16, v2
	v_fma_f32 v2, v68, s90, -v67
	v_exp_f32_e32 v17, v2
	v_fma_f32 v2, v69, s90, -v67
	v_exp_f32_e32 v18, v2
	v_fma_f32 v2, v71, s90, -v67
	v_exp_f32_e32 v68, v2
	v_fma_f32 v2, v54, s90, -v67
	v_exp_f32_e32 v69, v2
	v_fma_f32 v2, v55, s90, -v67
	v_exp_f32_e32 v71, v2
	v_fma_f32 v2, v56, s90, -v67
	v_exp_f32_e32 v88, v2
	v_fma_f32 v2, v57, s90, -v67
	v_exp_f32_e32 v89, v2
	v_fma_f32 v2, v58, s90, -v67
	v_exp_f32_e32 v185, v2
	v_fma_f32 v2, v59, s90, -v67
	v_exp_f32_e32 v190, v2
	v_fma_f32 v2, v60, s90, -v67
	v_exp_f32_e32 v191, v2
	v_fma_f32 v2, v61, s90, -v67
	v_exp_f32_e32 v192, v2
	v_fma_f32 v2, v62, s90, -v67
	v_exp_f32_e32 v194, v2
	v_fma_f32 v2, v63, s90, -v67
	v_exp_f32_e32 v195, v2
	v_fma_f32 v2, v64, s90, -v67
	s_waitcnt vmcnt(0)
	v_exp_f32_e32 v197, v2
	ds_read_b64_tr_b16 v[2:3], v91
	ds_read_b64_tr_b16 v[4:5], v91 offset:2048
	v_sub_f32_e32 v6, v66, v67
	v_exp_f32_e32 v198, v6
	v_cvt_pk_bf16_f32 v6, v16, v17
	v_cvt_pk_bf16_f32 v7, v18, v68
	v_cvt_pk_bf16_f32 v8, v69, v71
	v_cvt_pk_bf16_f32 v9, v88, v89
	v_add_u32_e32 v66, v153, v149
	ds_read_b64_tr_b16 v[10:11], v91 offset:4096
	ds_read_b64_tr_b16 v[12:13], v91 offset:6144
	s_waitcnt lgkmcnt(2)
	v_mfma_f32_32x32x16_bf16 v[50:65], v[2:5], v[6:9], 0
	ds_read_b64_tr_b16 v[2:3], v66
	ds_read_b64_tr_b16 v[4:5], v66 offset:2048
	v_fma_f32 v15, v31, s90, -v67
	v_cvt_pk_bf16_f32 v186, v185, v190
	v_cvt_pk_bf16_f32 v187, v191, v192
	v_cvt_pk_bf16_f32 v188, v194, v195
	v_cvt_pk_bf16_f32 v189, v197, v198
	v_exp_f32_e32 v182, v15
	s_waitcnt lgkmcnt(0)
	v_mfma_f32_32x32x16_bf16 v[34:49], v[2:5], v[6:9], 0
	v_fma_f32 v2, v32, s90, -v67
	v_exp_f32_e32 v183, v2
	v_fma_f32 v2, v33, s90, -v67
	v_exp_f32_e32 v184, v2
	v_mfma_f32_32x32x16_bf16 v[50:65], v[10:13], v[186:189], v[50:65]
	v_add_f32_e32 v10, v179, v14
	v_add_f32_e32 v10, v180, v10
	v_add_f32_e32 v10, v181, v10
	v_add_f32_e32 v14, v182, v10
	ds_read_b64_tr_b16 v[10:11], v66 offset:4096
	ds_read_b64_tr_b16 v[12:13], v66 offset:6144
	ds_read_b64_tr_b16 v[2:3], v92
	ds_read_b64_tr_b16 v[4:5], v92 offset:2048
	s_waitcnt lgkmcnt(2)
	v_mfma_f32_32x32x16_bf16 v[34:49], v[10:13], v[186:189], v[34:49]
	v_add_f32_e32 v10, v183, v14
	v_add_f32_e32 v10, v184, v10
	v_add_f32_e32 v10, v16, v10
	v_add_f32_e32 v10, v17, v10
	v_add_f32_e32 v14, v18, v10
	ds_read_b64_tr_b16 v[10:11], v92 offset:4096
	ds_read_b64_tr_b16 v[12:13], v92 offset:6144
	s_waitcnt lgkmcnt(2)
	v_mfma_f32_32x32x16_bf16 v[18:33], v[2:5], v[6:9], 0
	v_add_f32_e32 v2, v68, v14
	v_add_f32_e32 v2, v69, v2
	v_add_f32_e32 v2, v71, v2
	v_add_f32_e32 v14, v88, v2
	ds_read_b64_tr_b16 v[2:3], v95
	ds_read_b64_tr_b16 v[4:5], v95 offset:2048
	v_cndmask_b32_e64 v71, 0, 1, s[94:95]
	s_waitcnt lgkmcnt(2)
	v_mfma_f32_32x32x16_bf16 v[18:33], v[10:13], v[186:189], v[18:33]
	v_add_f32_e32 v10, v89, v14
	v_add_f32_e32 v10, v185, v10
	v_add_f32_e32 v10, v190, v10
	v_add_f32_e32 v10, v191, v10
	v_add_f32_e32 v68, v192, v10
	ds_read_b64_tr_b16 v[190:191], v95 offset:4096
	ds_read_b64_tr_b16 v[192:193], v95 offset:6144
	v_add_f32_e32 v68, v194, v68
	s_waitcnt lgkmcnt(2)
	v_mfma_f32_32x32x16_bf16 v[2:17], v[2:5], v[6:9], 0
	v_add_f32_e32 v68, v195, v68
	v_add_f32_e32 v68, v197, v68
	v_add_f32_e32 v88, v198, v68
	ds_bpermute_b32 v89, v70, v88
	s_waitcnt lgkmcnt(0)
	v_or_b32_e32 v70, s78, v1
	v_lshl_add_u64 v[68:69], s[8:9], 0, v[104:105]
	s_waitcnt lgkmcnt(1)
	v_mfma_f32_32x32x16_bf16 v[2:17], v[190:193], v[186:189], v[2:17]
	v_cmp_ne_u32_e64 s[8:9], 1, v71
	s_cbranch_vccnz .LBB0_272
	v_ashrrev_i32_e32 v71, 31, v70
	v_lshlrev_b64 v[186:187], 8, v[70:71]
	v_lshl_add_u64 v[186:187], v[68:69], 0, v[186:187]
	s_mov_b64 s[78:79], 0x4000
	v_lshl_add_u64 v[188:189], v[186:187], 0, s[78:79]
	s_mov_b32 s78, m0
	s_mov_b32 m0, s15
	s_nop 0
	global_load_lds_dwordx4 v[188:189], off
	s_mov_b32 m0, s78
	s_mov_b64 s[78:79], 0x4400
	v_lshl_add_u64 v[188:189], v[186:187], 0, s[78:79]
	s_mov_b32 s78, m0
	s_mov_b32 m0, s91
	s_nop 0
	global_load_lds_dwordx4 v[188:189], off
	s_mov_b32 m0, s78
	s_mov_b64 s[78:79], 0x4800
	v_lshl_add_u64 v[188:189], v[186:187], 0, s[78:79]
	s_mov_b32 s78, m0
	s_mov_b32 m0, s26
	s_nop 0
	global_load_lds_dwordx4 v[188:189], off
	s_mov_b32 m0, s78
	s_mov_b64 s[78:79], 0x4c00
	v_lshl_add_u64 v[188:189], v[186:187], 0, s[78:79]
	s_mov_b32 s78, m0
	s_mov_b32 m0, s27
	s_nop 0
	global_load_lds_dwordx4 v[188:189], off
	s_mov_b32 m0, s78
	s_mov_b64 s[78:79], 0x5000
	v_lshl_add_u64 v[188:189], v[186:187], 0, s[78:79]
	s_mov_b32 s78, m0
	s_mov_b32 m0, s28
	s_nop 0
	global_load_lds_dwordx4 v[188:189], off
	s_mov_b32 m0, s78
	s_mov_b64 s[78:79], 0x5400
	v_lshl_add_u64 v[188:189], v[186:187], 0, s[78:79]
	s_mov_b32 s78, m0
	s_mov_b32 m0, s29
	s_nop 0
	global_load_lds_dwordx4 v[188:189], off
	s_mov_b32 m0, s78
	s_mov_b64 s[78:79], 0x5800
	v_lshl_add_u64 v[188:189], v[186:187], 0, s[78:79]
	s_mov_b32 s78, m0
	s_mov_b32 m0, s30
	s_nop 0
	global_load_lds_dwordx4 v[188:189], off
	s_mov_b32 m0, s78
	s_mov_b64 s[78:79], 0x5c00
	v_lshl_add_u64 v[186:187], v[186:187], 0, s[78:79]
	s_mov_b32 s78, m0
	s_mov_b32 m0, s31
	s_nop 0
	global_load_lds_dwordx4 v[186:187], off
	s_mov_b32 m0, s78
